# v22: K tile DMA issue moved into MFMA shadows (group A after first QK MFMA pair, group B in P.V gaps 4-5)
# speedup vs baseline: 1.0111x; 1.0111x over previous
; #define SBAR() __builtin_amdgcn_sched_barrier(0)
; #define PVR(S, DA, DB, vbase) do { S[0] = tr_read<v_rd_off(DA, 0, 0)>(vbase); S[1] = tr_read<v_rd_off(DA, 0, 1)>(vbase); S[2] = tr_read<v_rd_off(DB, 0, 0)>(vbase); S[3] = tr_read<v_rd_off(DB, 0, 1)>(vbase); \
;     S[4] = tr_read<v_rd_off(DA, 1, 0)>(vbase); S[5] = tr_read<v_rd_off(DA, 1, 1)>(vbase); S[6] = tr_read<v_rd_off(DB, 1, 0)>(vbase); S[7] = tr_read<v_rd_off(DB, 1, 1)>(vbase); } while (0)
; #define RAWBAR() do { asm volatile("s_waitcnt lgkmcnt(0)" ::: "memory"); __builtin_amdgcn_s_barrier(); asm volatile("" ::: "memory"); } while (0)
; #define RAWBAR() do { asm volatile("s_waitcnt lgkmcnt(0)" ::: "memory"); __builtin_amdgcn_s_barrier(); asm volatile("" ::: "memory"); } while (0)
; #define RAWBAR() do { asm volatile("s_waitcnt lgkmcnt(0)" ::: "memory"); __builtin_amdgcn_s_barrier(); asm volatile("" ::: "memory"); } while (0)
; #define RAWBAR() do { asm volatile("s_waitcnt lgkmcnt(0)" ::: "memory"); __builtin_amdgcn_s_barrier(); asm volatile("" ::: "memory"); } while (0)
; #define RAWBAR() do { asm volatile("s_waitcnt lgkmcnt(0)" ::: "memory"); __builtin_amdgcn_s_barrier(); asm volatile("" ::: "memory"); } while (0)
; template <int MODE> ...
;     ...
;   for (int j = 0; j < NT; ++j) {
;     const int buf = j & 1;
;     if (j + 1 < NT) { STAGE((j + 1) * KVBLK, buf ^ 1); }
;     const char* Kb = K_lds + buf * 16384;
;     f32x16 pe = {}, po = {};
; #pragma unroll
;     for (int d0 = 0; d0 < 8; d0 += 2) {
;       const bf16x8 k0 = *reinterpret_cast<const bf16x8*>(Kb + KSWZ(krow, (d0 * 16 + hi * 8) * 2));
;       const bf16x8 k1 = *reinterpret_cast<const bf16x8*>(Kb + KSWZ(krow, ((d0 + 1) * 16 + hi * 8) * 2));
;       pe = __builtin_amdgcn_mfma_f32_32x32x16_bf16(k0, qr[d0], pe, 0, 0, 0);
;       po = __builtin_amdgcn_mfma_f32_32x32x16_bf16(k1, qr[d0 + 1], po, 0, 0, 0); }
;     const int vo = vb0 + buf * 32768;
;     s16x4 R0_[8], R1_[8];
;     PVR(R0_, 0, 1, vo);
;     f32x16 p;
; #pragma unroll
;     for (int r = 0; r < 16; ++r) p[r] = __builtin_amdgcn_exp2f(fmaf(pe[r] + po[r], C, negMc));
;     float ps = 0.f;
; #pragma unroll
;     for (int r = 0; r < 16; ++r) ps += p[r];
;     lsum += ps;
;     const bf16x8 own0 = pk8(p, 0), own1 = pk8(p, 8);
;     SBAR();
;     PV_TAIL4(o, vo, vo + 16384, own0, own1);
;     asm volatile("s_waitcnt vmcnt(0)" ::: "memory");
;     RAWBAR();
;   }
.LBB0_1019:
	ds_read_b128 v[226:229], v225 offset:16384
	ds_read_b128 v[230:233], v223 offset:16384
	ds_read_b128 v[234:237], v222 offset:16384
	ds_read_b128 v[238:241], v221 offset:16384
	v_exp_f32_e32 v144, v144
	v_exp_f32_e32 v145, v145
	v_exp_f32_e32 v146, v146
	v_exp_f32_e32 v147, v147
	s_waitcnt lgkmcnt(2)
	v_mfma_f32_32x32x16_bf16 v[128:143], v[226:229], v[188:191], 0
	v_mfma_f32_32x32x16_bf16 v[128:143], v[230:233], v[184:187], v[128:143]
	ds_read_b128 v[226:229], v202 offset:16384
	ds_read_b128 v[230:233], v203 offset:16384
	s_mov_b32 m0, s24
	s_nop 0
	global_load_lds_dwordx4 v220, s[86:87] sc1
	s_add_i32 m0, s24, 0x2000
	s_nop 0
	global_load_lds_dwordx4 v219, s[86:87] sc1
	v_exp_f32_e32 v148, v148
	v_exp_f32_e32 v149, v149
	v_exp_f32_e32 v150, v150
	v_exp_f32_e32 v151, v151
	v_add_f32_e32 v246, v144, v145
	v_add_f32_e32 v246, v146, v246
	v_add_f32_e32 v246, v147, v246
	s_waitcnt lgkmcnt(2)
	v_mfma_f32_32x32x16_bf16 v[128:143], v[234:237], v[180:183], v[128:143]
	v_mfma_f32_32x32x16_bf16 v[128:143], v[238:241], v[176:179], v[128:143]
	ds_read_b128 v[234:237], v204 offset:16384
	ds_read_b128 v[238:241], v205 offset:16384
	v_exp_f32_e32 v152, v152
	v_exp_f32_e32 v153, v153
	v_exp_f32_e32 v154, v154
	v_exp_f32_e32 v155, v155
	v_add_f32_e32 v246, v148, v246
	v_add_f32_e32 v246, v149, v246
	v_add_f32_e32 v246, v150, v246
	v_add_f32_e32 v246, v151, v246
	s_waitcnt lgkmcnt(2)
	v_mfma_f32_32x32x16_bf16 v[128:143], v[226:229], v[172:175], v[128:143]
	v_mfma_f32_32x32x16_bf16 v[128:143], v[230:233], v[168:171], v[128:143]
	v_exp_f32_e32 v156, v156
	v_exp_f32_e32 v157, v157
	v_exp_f32_e32 v158, v158
	v_exp_f32_e32 v159, v159
	v_add_f32_e32 v246, v152, v246
	v_add_f32_e32 v246, v153, v246
	v_add_f32_e32 v246, v154, v246
	v_add_f32_e32 v246, v155, v246
	v_cvt_pk_bf16_f32 v226, v144, v145
	v_cvt_pk_bf16_f32 v227, v146, v147
	v_cvt_pk_bf16_f32 v228, v148, v149
	v_cvt_pk_bf16_f32 v229, v150, v151
	s_waitcnt lgkmcnt(0)
	v_mfma_f32_32x32x16_bf16 v[128:143], v[234:237], v[164:167], v[128:143]
	v_mfma_f32_32x32x16_bf16 v[128:143], v[238:241], v[160:163], v[128:143]
	v_add_u32_e32 v245, s84, v214
	s_add_i32 s85, s84, 0x8000
	s_cmp_eq_u32 s85, 0x18000
	s_cselect_b32 s85, 0, s85
	ds_read_b64_tr_b16 v[234:235], v245 offset:0
	ds_read_b64_tr_b16 v[236:237], v245 offset:2048
	ds_read_b64_tr_b16 v[238:239], v245 offset:512
	ds_read_b64_tr_b16 v[240:241], v245 offset:2560
	ds_read_b64_tr_b16 v[144:145], v245 offset:4096
	ds_read_b64_tr_b16 v[146:147], v245 offset:6144
	ds_read_b64_tr_b16 v[148:149], v245 offset:4608
	ds_read_b64_tr_b16 v[150:151], v245 offset:6656
	v_add_f32_e32 v246, v156, v246
	v_add_f32_e32 v246, v157, v246
	v_add_f32_e32 v246, v158, v246
	v_add_f32_e32 v246, v159, v246
	v_cvt_pk_bf16_f32 v230, v152, v153
	v_cvt_pk_bf16_f32 v231, v154, v155
	v_cvt_pk_bf16_f32 v232, v156, v157
	v_cvt_pk_bf16_f32 v233, v158, v159
	v_add_f32_e32 v215, v215, v246
	ds_read_b64_tr_b16 v[152:153], v245 offset:1024
	ds_read_b64_tr_b16 v[154:155], v245 offset:3072
	ds_read_b64_tr_b16 v[156:157], v245 offset:1536
	ds_read_b64_tr_b16 v[158:159], v245 offset:3584
	s_waitcnt lgkmcnt(8)
	v_mfma_f32_32x32x16_bf16 v[112:127], v[226:229], v[234:237], v[112:127]
	v_mfma_f32_32x32x16_bf16 v[96:111], v[226:229], v[238:241], v[96:111]
	ds_read_b64_tr_b16 v[234:235], v245 offset:5120
	ds_read_b64_tr_b16 v[236:237], v245 offset:7168
	ds_read_b64_tr_b16 v[238:239], v245 offset:5632
	ds_read_b64_tr_b16 v[240:241], v245 offset:7680
	s_add_i32 s41, s85, s24
	s_add_i32 m0, s41, 0x8000
	s_nop 0
	global_load_lds_dwordx4 v218, s[2:3] sc1
	s_waitcnt lgkmcnt(8)
	v_mfma_f32_32x32x16_bf16 v[112:127], v[230:233], v[144:147], v[112:127]
	v_mfma_f32_32x32x16_bf16 v[96:111], v[230:233], v[148:151], v[96:111]
	ds_read_b64_tr_b16 v[144:145], v245 offset:16384
	ds_read_b64_tr_b16 v[146:147], v245 offset:18432
	ds_read_b64_tr_b16 v[148:149], v245 offset:16896
	ds_read_b64_tr_b16 v[150:151], v245 offset:18944
	s_add_i32 s41, s85, s24
	s_add_i32 m0, s41, 0xa000
	s_nop 0
	global_load_lds_dwordx4 v217, s[2:3] sc1
	s_waitcnt lgkmcnt(8)
	v_mfma_f32_32x32x16_bf16 v[80:95], v[226:229], v[152:155], v[80:95]
	v_mfma_f32_32x32x16_bf16 v[64:79], v[226:229], v[156:159], v[64:79]
	ds_read_b64_tr_b16 v[152:153], v245 offset:20480
	ds_read_b64_tr_b16 v[154:155], v245 offset:22528
	ds_read_b64_tr_b16 v[156:157], v245 offset:20992
	ds_read_b64_tr_b16 v[158:159], v245 offset:23040
	s_add_i32 s41, s85, s24
	s_add_i32 m0, s41, 0xc000
	s_nop 0
	global_load_lds_dwordx4 v242, s[2:3] sc1
	s_waitcnt lgkmcnt(8)
	v_mfma_f32_32x32x16_bf16 v[80:95], v[230:233], v[234:237], v[80:95]
	v_mfma_f32_32x32x16_bf16 v[64:79], v[230:233], v[238:241], v[64:79]
	ds_read_b64_tr_b16 v[234:235], v245 offset:17408
	ds_read_b64_tr_b16 v[236:237], v245 offset:19456
	ds_read_b64_tr_b16 v[238:239], v245 offset:17920
	ds_read_b64_tr_b16 v[240:241], v245 offset:19968
	s_add_i32 s41, s85, s24
	s_add_i32 m0, s41, 0xe000
	s_nop 0
	global_load_lds_dwordx4 v243, s[2:3] sc1
	s_waitcnt lgkmcnt(8)
	v_mfma_f32_32x32x16_bf16 v[48:63], v[226:229], v[144:147], v[48:63]
	v_mfma_f32_32x32x16_bf16 v[32:47], v[226:229], v[148:151], v[32:47]
	ds_read_b64_tr_b16 v[144:145], v245 offset:21504
	ds_read_b64_tr_b16 v[146:147], v245 offset:23552
	ds_read_b64_tr_b16 v[148:149], v245 offset:22016
	ds_read_b64_tr_b16 v[150:151], v245 offset:24064
	s_waitcnt lgkmcnt(8)
	v_mfma_f32_32x32x16_bf16 v[48:63], v[230:233], v[152:155], v[48:63]
	v_mfma_f32_32x32x16_bf16 v[32:47], v[230:233], v[156:159], v[32:47]
	s_waitcnt lgkmcnt(0)
	v_mfma_f32_32x32x16_bf16 v[16:31], v[226:229], v[234:237], v[16:31]
	s_waitcnt vmcnt(0)
	s_barrier
; #define SBAR() __builtin_amdgcn_sched_barrier(0)
; #define PVR(S, DA, DB, vbase) do { S[0] = tr_read<v_rd_off(DA, 0, 0)>(vbase); S[1] = tr_read<v_rd_off(DA, 0, 1)>(vbase); S[2] = tr_read<v_rd_off(DB, 0, 0)>(vbase); S[3] = tr_read<v_rd_off(DB, 0, 1)>(vbase); \
;     S[4] = tr_read<v_rd_off(DA, 1, 0)>(vbase); S[5] = tr_read<v_rd_off(DA, 1, 1)>(vbase); S[6] = tr_read<v_rd_off(DB, 1, 0)>(vbase); S[7] = tr_read<v_rd_off(DB, 1, 1)>(vbase); } while (0)
; #define RAWBAR() do { asm volatile("s_waitcnt lgkmcnt(0)" ::: "memory"); __builtin_amdgcn_s_barrier(); asm volatile("" ::: "memory"); } while (0)
; #define RAWBAR() do { asm volatile("s_waitcnt lgkmcnt(0)" ::: "memory"); __builtin_amdgcn_s_barrier(); asm volatile("" ::: "memory"); } while (0)
; #define RAWBAR() do { asm volatile("s_waitcnt lgkmcnt(0)" ::: "memory"); __builtin_amdgcn_s_barrier(); asm volatile("" ::: "memory"); } while (0)
; #define RAWBAR() do { asm volatile("s_waitcnt lgkmcnt(0)" ::: "memory"); __builtin_amdgcn_s_barrier(); asm volatile("" ::: "memory"); } while (0)
; #define RAWBAR() do { asm volatile("s_waitcnt lgkmcnt(0)" ::: "memory"); __builtin_amdgcn_s_barrier(); asm volatile("" ::: "memory"); } while (0)
; template <int MODE> ...
;     ...
;   for (int j = 0; j < NT; ++j) {
;     const int buf = j & 1;
;     if (j + 1 < NT) { STAGE((j + 1) * KVBLK, buf ^ 1); }
;     const char* Kb = K_lds + buf * 16384;
;     f32x16 pe = {}, po = {};
; #pragma unroll
;     for (int d0 = 0; d0 < 8; d0 += 2) {
;       const bf16x8 k0 = *reinterpret_cast<const bf16x8*>(Kb + KSWZ(krow, (d0 * 16 + hi * 8) * 2));
;       const bf16x8 k1 = *reinterpret_cast<const bf16x8*>(Kb + KSWZ(krow, ((d0 + 1) * 16 + hi * 8) * 2));
;       pe = __builtin_amdgcn_mfma_f32_32x32x16_bf16(k0, qr[d0], pe, 0, 0, 0);
;       po = __builtin_amdgcn_mfma_f32_32x32x16_bf16(k1, qr[d0 + 1], po, 0, 0, 0); }
;     const int vo = vb0 + buf * 32768;
;     s16x4 R0_[8], R1_[8];
;     PVR(R0_, 0, 1, vo);
;     f32x16 p;
; #pragma unroll
;     for (int r = 0; r < 16; ++r) p[r] = __builtin_amdgcn_exp2f(fmaf(pe[r] + po[r], C, negMc));
;     float ps = 0.f;
; #pragma unroll
;     for (int r = 0; r < 16; ++r) ps += p[r];
;     lsum += ps;
;     const bf16x8 own0 = pk8(p, 0), own1 = pk8(p, 8);
;     SBAR();
;     PV_TAIL4(o, vo, vo + 16384, own0, own1);
;     asm volatile("s_waitcnt vmcnt(0)" ::: "memory");
;     RAWBAR();
;   }
	s_add_u32 s86, s86, 0x4000
	s_addc_u32 s87, s87, 0
	s_add_u32 s2, s2, 0x8000
	s_addc_u32 s3, s3, 0
	v_mfma_f32_32x32x16_bf16 v[0:15], v[226:229], v[238:241], v[0:15]
	v_mfma_f32_32x32x16_bf16 v[16:31], v[230:233], v[144:147], v[16:31]
	v_mfma_f32_32x32x16_bf16 v[0:15], v[230:233], v[148:151], v[0:15]
	s_add_i32 s84, s84, 0x8000
	s_cmp_eq_u32 s84, 0x18000
	s_cselect_b32 s84, 0, s84
	ds_read_b128 v[226:229], v225 offset:0
	ds_read_b128 v[230:233], v223 offset:0
	ds_read_b128 v[234:237], v222 offset:0
	ds_read_b128 v[238:241], v221 offset:0
	v_exp_f32_e32 v128, v128
	v_exp_f32_e32 v129, v129
	v_exp_f32_e32 v130, v130
	v_exp_f32_e32 v131, v131
	s_waitcnt lgkmcnt(2)
	v_mfma_f32_32x32x16_bf16 v[144:159], v[226:229], v[188:191], 0
	v_mfma_f32_32x32x16_bf16 v[144:159], v[230:233], v[184:187], v[144:159]
	ds_read_b128 v[226:229], v202 offset:0
	ds_read_b128 v[230:233], v203 offset:0
	s_add_i32 m0, s24, 0x4000
	s_nop 0
	global_load_lds_dwordx4 v220, s[86:87] sc1
	s_add_i32 m0, s24, 0x6000
	s_nop 0
	global_load_lds_dwordx4 v219, s[86:87] sc1
	v_exp_f32_e32 v132, v132
	v_exp_f32_e32 v133, v133
	v_exp_f32_e32 v134, v134
	v_exp_f32_e32 v135, v135
	v_add_f32_e32 v246, v128, v129
	v_add_f32_e32 v246, v130, v246
	v_add_f32_e32 v246, v131, v246
	s_waitcnt lgkmcnt(2)
	v_mfma_f32_32x32x16_bf16 v[144:159], v[234:237], v[180:183], v[144:159]
	v_mfma_f32_32x32x16_bf16 v[144:159], v[238:241], v[176:179], v[144:159]
	ds_read_b128 v[234:237], v204 offset:0
	ds_read_b128 v[238:241], v205 offset:0
	v_exp_f32_e32 v136, v136
	v_exp_f32_e32 v137, v137
	v_exp_f32_e32 v138, v138
	v_exp_f32_e32 v139, v139
	v_add_f32_e32 v246, v132, v246
	v_add_f32_e32 v246, v133, v246
	v_add_f32_e32 v246, v134, v246
	v_add_f32_e32 v246, v135, v246
	s_waitcnt lgkmcnt(2)
	v_mfma_f32_32x32x16_bf16 v[144:159], v[226:229], v[172:175], v[144:159]
	v_mfma_f32_32x32x16_bf16 v[144:159], v[230:233], v[168:171], v[144:159]
	v_exp_f32_e32 v140, v140
	v_exp_f32_e32 v141, v141
	v_exp_f32_e32 v142, v142
	v_exp_f32_e32 v143, v143
	v_add_f32_e32 v246, v136, v246
	v_add_f32_e32 v246, v137, v246
	v_add_f32_e32 v246, v138, v246
	v_add_f32_e32 v246, v139, v246
	v_cvt_pk_bf16_f32 v226, v128, v129
	v_cvt_pk_bf16_f32 v227, v130, v131
	v_cvt_pk_bf16_f32 v228, v132, v133
	v_cvt_pk_bf16_f32 v229, v134, v135
	s_waitcnt lgkmcnt(0)
	v_mfma_f32_32x32x16_bf16 v[144:159], v[234:237], v[164:167], v[144:159]
	v_mfma_f32_32x32x16_bf16 v[144:159], v[238:241], v[160:163], v[144:159]
	v_add_u32_e32 v245, s84, v214
	s_add_i32 s85, s84, 0x8000
	s_cmp_eq_u32 s85, 0x18000
	s_cselect_b32 s85, 0, s85
	ds_read_b64_tr_b16 v[234:235], v245 offset:0
	ds_read_b64_tr_b16 v[236:237], v245 offset:2048
	ds_read_b64_tr_b16 v[238:239], v245 offset:512
	ds_read_b64_tr_b16 v[240:241], v245 offset:2560
	ds_read_b64_tr_b16 v[128:129], v245 offset:4096
	ds_read_b64_tr_b16 v[130:131], v245 offset:6144
	ds_read_b64_tr_b16 v[132:133], v245 offset:4608
	ds_read_b64_tr_b16 v[134:135], v245 offset:6656
	v_add_f32_e32 v246, v140, v246
	v_add_f32_e32 v246, v141, v246
	v_add_f32_e32 v246, v142, v246
	v_add_f32_e32 v246, v143, v246
	v_cvt_pk_bf16_f32 v230, v136, v137
	v_cvt_pk_bf16_f32 v231, v138, v139
	v_cvt_pk_bf16_f32 v232, v140, v141
	v_cvt_pk_bf16_f32 v233, v142, v143
	v_add_f32_e32 v215, v215, v246
	ds_read_b64_tr_b16 v[136:137], v245 offset:1024
	ds_read_b64_tr_b16 v[138:139], v245 offset:3072
	ds_read_b64_tr_b16 v[140:141], v245 offset:1536
	ds_read_b64_tr_b16 v[142:143], v245 offset:3584
	s_waitcnt lgkmcnt(8)
	v_mfma_f32_32x32x16_bf16 v[112:127], v[226:229], v[234:237], v[112:127]
	v_mfma_f32_32x32x16_bf16 v[96:111], v[226:229], v[238:241], v[96:111]
	ds_read_b64_tr_b16 v[234:235], v245 offset:5120
	ds_read_b64_tr_b16 v[236:237], v245 offset:7168
	ds_read_b64_tr_b16 v[238:239], v245 offset:5632
	ds_read_b64_tr_b16 v[240:241], v245 offset:7680
	s_add_i32 s41, s85, s24
	s_add_i32 m0, s41, 0x8000
	s_nop 0
	global_load_lds_dwordx4 v218, s[2:3] sc1
	s_waitcnt lgkmcnt(8)
	v_mfma_f32_32x32x16_bf16 v[112:127], v[230:233], v[128:131], v[112:127]
	v_mfma_f32_32x32x16_bf16 v[96:111], v[230:233], v[132:135], v[96:111]
	ds_read_b64_tr_b16 v[128:129], v245 offset:16384
	ds_read_b64_tr_b16 v[130:131], v245 offset:18432
	ds_read_b64_tr_b16 v[132:133], v245 offset:16896
	ds_read_b64_tr_b16 v[134:135], v245 offset:18944
	s_add_i32 s41, s85, s24
	s_add_i32 m0, s41, 0xa000
	s_nop 0
	global_load_lds_dwordx4 v217, s[2:3] sc1
	s_waitcnt lgkmcnt(8)
	v_mfma_f32_32x32x16_bf16 v[80:95], v[226:229], v[136:139], v[80:95]
	v_mfma_f32_32x32x16_bf16 v[64:79], v[226:229], v[140:143], v[64:79]
	ds_read_b64_tr_b16 v[136:137], v245 offset:20480
	ds_read_b64_tr_b16 v[138:139], v245 offset:22528
	ds_read_b64_tr_b16 v[140:141], v245 offset:20992
	ds_read_b64_tr_b16 v[142:143], v245 offset:23040
	s_add_i32 s41, s85, s24
	s_add_i32 m0, s41, 0xc000
	s_nop 0
	global_load_lds_dwordx4 v242, s[2:3] sc1
	s_waitcnt lgkmcnt(8)
	v_mfma_f32_32x32x16_bf16 v[80:95], v[230:233], v[234:237], v[80:95]
	v_mfma_f32_32x32x16_bf16 v[64:79], v[230:233], v[238:241], v[64:79]
	ds_read_b64_tr_b16 v[234:235], v245 offset:17408
	ds_read_b64_tr_b16 v[236:237], v245 offset:19456
	ds_read_b64_tr_b16 v[238:239], v245 offset:17920
	ds_read_b64_tr_b16 v[240:241], v245 offset:19968
	s_add_i32 s41, s85, s24
	s_add_i32 m0, s41, 0xe000
	s_nop 0
	global_load_lds_dwordx4 v243, s[2:3] sc1
	s_waitcnt lgkmcnt(8)
	v_mfma_f32_32x32x16_bf16 v[48:63], v[226:229], v[128:131], v[48:63]
	v_mfma_f32_32x32x16_bf16 v[32:47], v[226:229], v[132:135], v[32:47]
	ds_read_b64_tr_b16 v[128:129], v245 offset:21504
	ds_read_b64_tr_b16 v[130:131], v245 offset:23552
	ds_read_b64_tr_b16 v[132:133], v245 offset:22016
	ds_read_b64_tr_b16 v[134:135], v245 offset:24064
	s_waitcnt lgkmcnt(8)
	v_mfma_f32_32x32x16_bf16 v[48:63], v[230:233], v[136:139], v[48:63]
	v_mfma_f32_32x32x16_bf16 v[32:47], v[230:233], v[140:143], v[32:47]
	s_waitcnt lgkmcnt(0)
	v_mfma_f32_32x32x16_bf16 v[16:31], v[226:229], v[234:237], v[16:31]
	s_waitcnt vmcnt(0)
	s_barrier
	s_add_u32 s86, s86, 0x4000
	s_addc_u32 s87, s87, 0
	s_add_u32 s2, s2, 0x8000
	s_addc_u32 s3, s3, 0
	v_mfma_f32_32x32x16_bf16 v[0:15], v[226:229], v[238:241], v[0:15]
	v_mfma_f32_32x32x16_bf16 v[16:31], v[230:233], v[128:131], v[16:31]
	v_mfma_f32_32x32x16_bf16 v[0:15], v[230:233], v[132:135], v[0:15]
	s_add_i32 s84, s84, 0x8000
	s_cmp_eq_u32 s84, 0x18000
	s_cselect_b32 s84, 0, s84
	s_add_i32 s25, s25, 1
	s_cmpk_eq_i32 s25, 0x82
	s_cbranch_scc0 .LBB0_1019
	s_barrier
	s_branch .Lattn_join_m0

; #define SBAR() __builtin_amdgcn_sched_barrier(0)
; #define PVR(S, DA, DB, vbase) do { S[0] = tr_read<v_rd_off(DA, 0, 0)>(vbase); S[1] = tr_read<v_rd_off(DA, 0, 1)>(vbase); S[2] = tr_read<v_rd_off(DB, 0, 0)>(vbase); S[3] = tr_read<v_rd_off(DB, 0, 1)>(vbase); \
;     S[4] = tr_read<v_rd_off(DA, 1, 0)>(vbase); S[5] = tr_read<v_rd_off(DA, 1, 1)>(vbase); S[6] = tr_read<v_rd_off(DB, 1, 0)>(vbase); S[7] = tr_read<v_rd_off(DB, 1, 1)>(vbase); } while (0)
; #define RAWBAR() do { asm volatile("s_waitcnt lgkmcnt(0)" ::: "memory"); __builtin_amdgcn_s_barrier(); asm volatile("" ::: "memory"); } while (0)
; #define RAWBAR() do { asm volatile("s_waitcnt lgkmcnt(0)" ::: "memory"); __builtin_amdgcn_s_barrier(); asm volatile("" ::: "memory"); } while (0)
; #define RAWBAR() do { asm volatile("s_waitcnt lgkmcnt(0)" ::: "memory"); __builtin_amdgcn_s_barrier(); asm volatile("" ::: "memory"); } while (0)
; #define RAWBAR() do { asm volatile("s_waitcnt lgkmcnt(0)" ::: "memory"); __builtin_amdgcn_s_barrier(); asm volatile("" ::: "memory"); } while (0)
; #define RAWBAR() do { asm volatile("s_waitcnt lgkmcnt(0)" ::: "memory"); __builtin_amdgcn_s_barrier(); asm volatile("" ::: "memory"); } while (0)
; template <int MODE> ...
;     ...
;   for (int j = 0; j < NT; ++j) {
;     const int buf = j & 1;
;     if (j + 1 < NT) { STAGE((j + 1) * KVBLK, buf ^ 1); }
;     const char* Kb = K_lds + buf * 16384;
;     f32x16 pe = {}, po = {};
; #pragma unroll
;     for (int d0 = 0; d0 < 8; d0 += 2) {
;       const bf16x8 k0 = *reinterpret_cast<const bf16x8*>(Kb + KSWZ(krow, (d0 * 16 + hi * 8) * 2));
;       const bf16x8 k1 = *reinterpret_cast<const bf16x8*>(Kb + KSWZ(krow, ((d0 + 1) * 16 + hi * 8) * 2));
;       pe = __builtin_amdgcn_mfma_f32_32x32x16_bf16(k0, qr[d0], pe, 0, 0, 0);
;       po = __builtin_amdgcn_mfma_f32_32x32x16_bf16(k1, qr[d0 + 1], po, 0, 0, 0); }
;     const int vo = vb0 + buf * 32768;
;     s16x4 R0_[8], R1_[8];
;     PVR(R0_, 0, 1, vo);
;     f32x16 p;
; #pragma unroll
;     for (int r = 0; r < 16; ++r) p[r] = __builtin_amdgcn_exp2f(fmaf(pe[r] + po[r], C, negMc));
;     float ps = 0.f;
; #pragma unroll
;     for (int r = 0; r < 16; ++r) ps += p[r];
;     lsum += ps;
;     const bf16x8 own0 = pk8(p, 0), own1 = pk8(p, 8);
;     SBAR();
;     PV_TAIL4(o, vo, vo + 16384, own0, own1);
;     asm volatile("s_waitcnt vmcnt(0)" ::: "memory");
;     RAWBAR();
;   }
.LattnB_m0:
	ds_read_b128 v[226:229], v225 offset:16384
	ds_read_b128 v[230:233], v223 offset:16384
	ds_read_b128 v[234:237], v222 offset:16384
	ds_read_b128 v[238:241], v221 offset:16384
	v_exp_f32_e32 v144, v144
	v_exp_f32_e32 v145, v145
	v_exp_f32_e32 v146, v146
	v_exp_f32_e32 v147, v147
	s_waitcnt lgkmcnt(2)
	v_mfma_f32_32x32x16_bf16 v[128:143], v[226:229], v[188:191], 0
	v_mfma_f32_32x32x16_bf16 v[128:143], v[230:233], v[184:187], v[128:143]
	ds_read_b128 v[226:229], v202 offset:16384
	ds_read_b128 v[230:233], v203 offset:16384
	v_exp_f32_e32 v148, v148
	v_exp_f32_e32 v149, v149
	v_exp_f32_e32 v150, v150
	v_exp_f32_e32 v151, v151
	v_add_f32_e32 v246, v144, v145
	v_add_f32_e32 v246, v146, v246
	v_add_f32_e32 v246, v147, v246
	s_waitcnt lgkmcnt(2)
	v_mfma_f32_32x32x16_bf16 v[128:143], v[234:237], v[180:183], v[128:143]
	v_mfma_f32_32x32x16_bf16 v[128:143], v[238:241], v[176:179], v[128:143]
	ds_read_b128 v[234:237], v204 offset:16384
	ds_read_b128 v[238:241], v205 offset:16384
	v_exp_f32_e32 v152, v152
	v_exp_f32_e32 v153, v153
	v_exp_f32_e32 v154, v154
	v_exp_f32_e32 v155, v155
	v_add_f32_e32 v246, v148, v246
	v_add_f32_e32 v246, v149, v246
	v_add_f32_e32 v246, v150, v246
	v_add_f32_e32 v246, v151, v246
	s_waitcnt lgkmcnt(2)
	v_mfma_f32_32x32x16_bf16 v[128:143], v[226:229], v[172:175], v[128:143]
	v_mfma_f32_32x32x16_bf16 v[128:143], v[230:233], v[168:171], v[128:143]
	v_exp_f32_e32 v156, v156
	v_exp_f32_e32 v157, v157
	v_exp_f32_e32 v158, v158
	v_exp_f32_e32 v159, v159
	v_add_f32_e32 v246, v152, v246
	v_add_f32_e32 v246, v153, v246
	v_add_f32_e32 v246, v154, v246
	v_add_f32_e32 v246, v155, v246
	v_cvt_pk_bf16_f32 v226, v144, v145
	v_cvt_pk_bf16_f32 v227, v146, v147
	v_cvt_pk_bf16_f32 v228, v148, v149
	v_cvt_pk_bf16_f32 v229, v150, v151
	s_waitcnt lgkmcnt(0)
	v_mfma_f32_32x32x16_bf16 v[128:143], v[234:237], v[164:167], v[128:143]
	v_mfma_f32_32x32x16_bf16 v[128:143], v[238:241], v[160:163], v[128:143]
	s_waitcnt vmcnt(0)
	s_barrier
	s_add_u32 s86, s86, 0x4000
	s_addc_u32 s87, s87, 0
	s_add_u32 s2, s2, 0x8000
	s_addc_u32 s3, s3, 0
	v_add_u32_e32 v245, s84, v214
	s_sub_u32 s85, s84, 0x8000
	s_cmp_eq_u32 s84, 0
	s_cselect_b32 s85, 0x10000, s85
	ds_read_b64_tr_b16 v[234:235], v245 offset:0
	ds_read_b64_tr_b16 v[236:237], v245 offset:2048
	ds_read_b64_tr_b16 v[238:239], v245 offset:512
	ds_read_b64_tr_b16 v[240:241], v245 offset:2560
	ds_read_b64_tr_b16 v[144:145], v245 offset:4096
	ds_read_b64_tr_b16 v[146:147], v245 offset:6144
	ds_read_b64_tr_b16 v[148:149], v245 offset:4608
	ds_read_b64_tr_b16 v[150:151], v245 offset:6656
	v_add_f32_e32 v246, v156, v246
	v_add_f32_e32 v246, v157, v246
	v_add_f32_e32 v246, v158, v246
	v_add_f32_e32 v246, v159, v246
	v_cvt_pk_bf16_f32 v230, v152, v153
	v_cvt_pk_bf16_f32 v231, v154, v155
	v_cvt_pk_bf16_f32 v232, v156, v157
	v_cvt_pk_bf16_f32 v233, v158, v159
	v_add_f32_e32 v215, v215, v246
	ds_read_b64_tr_b16 v[152:153], v245 offset:1024
	ds_read_b64_tr_b16 v[154:155], v245 offset:3072
	ds_read_b64_tr_b16 v[156:157], v245 offset:1536
	ds_read_b64_tr_b16 v[158:159], v245 offset:3584
	s_waitcnt lgkmcnt(8)
	v_mfma_f32_32x32x16_bf16 v[112:127], v[226:229], v[234:237], v[112:127]
	v_mfma_f32_32x32x16_bf16 v[96:111], v[226:229], v[238:241], v[96:111]
	ds_read_b64_tr_b16 v[234:235], v245 offset:5120
	ds_read_b64_tr_b16 v[236:237], v245 offset:7168
	ds_read_b64_tr_b16 v[238:239], v245 offset:5632
	ds_read_b64_tr_b16 v[240:241], v245 offset:7680
	s_add_i32 s41, s85, s24
	s_add_i32 m0, s41, 0x8000
	s_nop 0
	global_load_lds_dwordx4 v218, s[2:3] sc1
	s_waitcnt lgkmcnt(8)
	v_mfma_f32_32x32x16_bf16 v[112:127], v[230:233], v[144:147], v[112:127]
	v_mfma_f32_32x32x16_bf16 v[96:111], v[230:233], v[148:151], v[96:111]
	ds_read_b64_tr_b16 v[144:145], v245 offset:16384
	ds_read_b64_tr_b16 v[146:147], v245 offset:18432
	ds_read_b64_tr_b16 v[148:149], v245 offset:16896
	ds_read_b64_tr_b16 v[150:151], v245 offset:18944
	s_add_i32 s41, s85, s24
	s_add_i32 m0, s41, 0xa000
	s_nop 0
	global_load_lds_dwordx4 v217, s[2:3] sc1
	s_waitcnt lgkmcnt(8)
	v_mfma_f32_32x32x16_bf16 v[80:95], v[226:229], v[152:155], v[80:95]
	v_mfma_f32_32x32x16_bf16 v[64:79], v[226:229], v[156:159], v[64:79]
	ds_read_b64_tr_b16 v[152:153], v245 offset:20480
	ds_read_b64_tr_b16 v[154:155], v245 offset:22528
	ds_read_b64_tr_b16 v[156:157], v245 offset:20992
	ds_read_b64_tr_b16 v[158:159], v245 offset:23040
	s_add_i32 s41, s85, s24
	s_add_i32 m0, s41, 0xc000
	s_nop 0
	global_load_lds_dwordx4 v242, s[2:3] sc1
	s_waitcnt lgkmcnt(8)
	v_mfma_f32_32x32x16_bf16 v[80:95], v[230:233], v[234:237], v[80:95]
	v_mfma_f32_32x32x16_bf16 v[64:79], v[230:233], v[238:241], v[64:79]
	ds_read_b64_tr_b16 v[234:235], v245 offset:17408
	ds_read_b64_tr_b16 v[236:237], v245 offset:19456
	ds_read_b64_tr_b16 v[238:239], v245 offset:17920
	ds_read_b64_tr_b16 v[240:241], v245 offset:19968
	s_add_i32 s41, s85, s24
	s_add_i32 m0, s41, 0xe000
	s_nop 0
	global_load_lds_dwordx4 v243, s[2:3] sc1
	s_waitcnt lgkmcnt(8)
	v_mfma_f32_32x32x16_bf16 v[48:63], v[226:229], v[144:147], v[48:63]
	v_mfma_f32_32x32x16_bf16 v[32:47], v[226:229], v[148:151], v[32:47]
	ds_read_b64_tr_b16 v[144:145], v245 offset:21504
	ds_read_b64_tr_b16 v[146:147], v245 offset:23552
	ds_read_b64_tr_b16 v[148:149], v245 offset:22016
	ds_read_b64_tr_b16 v[150:151], v245 offset:24064
	s_add_i32 m0, s24, 0x4000
	s_nop 0
	global_load_lds_dwordx4 v220, s[86:87] sc1
	s_waitcnt lgkmcnt(8)
	v_mfma_f32_32x32x16_bf16 v[48:63], v[230:233], v[152:155], v[48:63]
	v_mfma_f32_32x32x16_bf16 v[32:47], v[230:233], v[156:159], v[32:47]
	s_add_i32 m0, s24, 0x6000
	s_nop 0
	global_load_lds_dwordx4 v219, s[86:87] sc1
	s_waitcnt lgkmcnt(0)
; #define SBAR() __builtin_amdgcn_sched_barrier(0)
; #define PVR(S, DA, DB, vbase) do { S[0] = tr_read<v_rd_off(DA, 0, 0)>(vbase); S[1] = tr_read<v_rd_off(DA, 0, 1)>(vbase); S[2] = tr_read<v_rd_off(DB, 0, 0)>(vbase); S[3] = tr_read<v_rd_off(DB, 0, 1)>(vbase); \
;     S[4] = tr_read<v_rd_off(DA, 1, 0)>(vbase); S[5] = tr_read<v_rd_off(DA, 1, 1)>(vbase); S[6] = tr_read<v_rd_off(DB, 1, 0)>(vbase); S[7] = tr_read<v_rd_off(DB, 1, 1)>(vbase); } while (0)
; #define RAWBAR() do { asm volatile("s_waitcnt lgkmcnt(0)" ::: "memory"); __builtin_amdgcn_s_barrier(); asm volatile("" ::: "memory"); } while (0)
; #define RAWBAR() do { asm volatile("s_waitcnt lgkmcnt(0)" ::: "memory"); __builtin_amdgcn_s_barrier(); asm volatile("" ::: "memory"); } while (0)
; #define RAWBAR() do { asm volatile("s_waitcnt lgkmcnt(0)" ::: "memory"); __builtin_amdgcn_s_barrier(); asm volatile("" ::: "memory"); } while (0)
; #define RAWBAR() do { asm volatile("s_waitcnt lgkmcnt(0)" ::: "memory"); __builtin_amdgcn_s_barrier(); asm volatile("" ::: "memory"); } while (0)
; #define RAWBAR() do { asm volatile("s_waitcnt lgkmcnt(0)" ::: "memory"); __builtin_amdgcn_s_barrier(); asm volatile("" ::: "memory"); } while (0)
; template <int MODE> ...
;     ...
;   for (int j = 0; j < NT; ++j) {
;     const int buf = j & 1;
;     if (j + 1 < NT) { STAGE((j + 1) * KVBLK, buf ^ 1); }
;     const char* Kb = K_lds + buf * 16384;
;     f32x16 pe = {}, po = {};
; #pragma unroll
;     for (int d0 = 0; d0 < 8; d0 += 2) {
;       const bf16x8 k0 = *reinterpret_cast<const bf16x8*>(Kb + KSWZ(krow, (d0 * 16 + hi * 8) * 2));
;       const bf16x8 k1 = *reinterpret_cast<const bf16x8*>(Kb + KSWZ(krow, ((d0 + 1) * 16 + hi * 8) * 2));
;       pe = __builtin_amdgcn_mfma_f32_32x32x16_bf16(k0, qr[d0], pe, 0, 0, 0);
;       po = __builtin_amdgcn_mfma_f32_32x32x16_bf16(k1, qr[d0 + 1], po, 0, 0, 0); }
;     const int vo = vb0 + buf * 32768;
;     s16x4 R0_[8], R1_[8];
;     PVR(R0_, 0, 1, vo);
;     f32x16 p;
; #pragma unroll
;     for (int r = 0; r < 16; ++r) p[r] = __builtin_amdgcn_exp2f(fmaf(pe[r] + po[r], C, negMc));
;     float ps = 0.f;
; #pragma unroll
;     for (int r = 0; r < 16; ++r) ps += p[r];
;     lsum += ps;
;     const bf16x8 own0 = pk8(p, 0), own1 = pk8(p, 8);
;     SBAR();
;     PV_TAIL4(o, vo, vo + 16384, own0, own1);
;     asm volatile("s_waitcnt vmcnt(0)" ::: "memory");
;     RAWBAR();
;   }
	v_mfma_f32_32x32x16_bf16 v[16:31], v[226:229], v[234:237], v[16:31]
	v_mfma_f32_32x32x16_bf16 v[0:15], v[226:229], v[238:241], v[0:15]
	v_mfma_f32_32x32x16_bf16 v[16:31], v[230:233], v[144:147], v[16:31]
	v_mfma_f32_32x32x16_bf16 v[0:15], v[230:233], v[148:151], v[0:15]
	s_add_i32 s84, s84, 0x8000
	s_cmp_eq_u32 s84, 0x18000
	s_cselect_b32 s84, 0, s84
	ds_read_b128 v[226:229], v225 offset:0
	ds_read_b128 v[230:233], v223 offset:0
	ds_read_b128 v[234:237], v222 offset:0
	ds_read_b128 v[238:241], v221 offset:0
	v_exp_f32_e32 v128, v128
	v_exp_f32_e32 v129, v129
	v_exp_f32_e32 v130, v130
	v_exp_f32_e32 v131, v131
	s_waitcnt lgkmcnt(2)
	v_mfma_f32_32x32x16_bf16 v[144:159], v[226:229], v[188:191], 0
	v_mfma_f32_32x32x16_bf16 v[144:159], v[230:233], v[184:187], v[144:159]
	ds_read_b128 v[226:229], v202 offset:0
	ds_read_b128 v[230:233], v203 offset:0
	v_exp_f32_e32 v132, v132
	v_exp_f32_e32 v133, v133
	v_exp_f32_e32 v134, v134
	v_exp_f32_e32 v135, v135
	v_add_f32_e32 v246, v128, v129
	v_add_f32_e32 v246, v130, v246
	v_add_f32_e32 v246, v131, v246
	s_waitcnt lgkmcnt(2)
	v_mfma_f32_32x32x16_bf16 v[144:159], v[234:237], v[180:183], v[144:159]
	v_mfma_f32_32x32x16_bf16 v[144:159], v[238:241], v[176:179], v[144:159]
	ds_read_b128 v[234:237], v204 offset:0
	ds_read_b128 v[238:241], v205 offset:0
	v_exp_f32_e32 v136, v136
	v_exp_f32_e32 v137, v137
	v_exp_f32_e32 v138, v138
	v_exp_f32_e32 v139, v139
	v_add_f32_e32 v246, v132, v246
	v_add_f32_e32 v246, v133, v246
	v_add_f32_e32 v246, v134, v246
	v_add_f32_e32 v246, v135, v246
	s_waitcnt lgkmcnt(2)
	v_mfma_f32_32x32x16_bf16 v[144:159], v[226:229], v[172:175], v[144:159]
	v_mfma_f32_32x32x16_bf16 v[144:159], v[230:233], v[168:171], v[144:159]
	v_exp_f32_e32 v140, v140
	v_exp_f32_e32 v141, v141
	v_exp_f32_e32 v142, v142
	v_exp_f32_e32 v143, v143
	v_add_f32_e32 v246, v136, v246
	v_add_f32_e32 v246, v137, v246
	v_add_f32_e32 v246, v138, v246
	v_add_f32_e32 v246, v139, v246
	v_cvt_pk_bf16_f32 v226, v128, v129
	v_cvt_pk_bf16_f32 v227, v130, v131
	v_cvt_pk_bf16_f32 v228, v132, v133
	v_cvt_pk_bf16_f32 v229, v134, v135
	s_waitcnt lgkmcnt(0)
	v_mfma_f32_32x32x16_bf16 v[144:159], v[234:237], v[164:167], v[144:159]
	v_mfma_f32_32x32x16_bf16 v[144:159], v[238:241], v[160:163], v[144:159]
	s_waitcnt vmcnt(0)
	s_barrier
	s_add_u32 s86, s86, 0x4000
	s_addc_u32 s87, s87, 0
	s_add_u32 s2, s2, 0x8000
	s_addc_u32 s3, s3, 0
	v_add_u32_e32 v245, s84, v214
	s_sub_u32 s85, s84, 0x8000
	s_cmp_eq_u32 s84, 0
	s_cselect_b32 s85, 0x10000, s85
	ds_read_b64_tr_b16 v[234:235], v245 offset:0
	ds_read_b64_tr_b16 v[236:237], v245 offset:2048
	ds_read_b64_tr_b16 v[238:239], v245 offset:512
	ds_read_b64_tr_b16 v[240:241], v245 offset:2560
	ds_read_b64_tr_b16 v[128:129], v245 offset:4096
	ds_read_b64_tr_b16 v[130:131], v245 offset:6144
	ds_read_b64_tr_b16 v[132:133], v245 offset:4608
	ds_read_b64_tr_b16 v[134:135], v245 offset:6656
	v_add_f32_e32 v246, v140, v246
	v_add_f32_e32 v246, v141, v246
	v_add_f32_e32 v246, v142, v246
	v_add_f32_e32 v246, v143, v246
	v_cvt_pk_bf16_f32 v230, v136, v137
	v_cvt_pk_bf16_f32 v231, v138, v139
	v_cvt_pk_bf16_f32 v232, v140, v141
	v_cvt_pk_bf16_f32 v233, v142, v143
	v_add_f32_e32 v215, v215, v246
	ds_read_b64_tr_b16 v[136:137], v245 offset:1024
	ds_read_b64_tr_b16 v[138:139], v245 offset:3072
	ds_read_b64_tr_b16 v[140:141], v245 offset:1536
	ds_read_b64_tr_b16 v[142:143], v245 offset:3584
	s_waitcnt lgkmcnt(8)
	v_mfma_f32_32x32x16_bf16 v[112:127], v[226:229], v[234:237], v[112:127]
	v_mfma_f32_32x32x16_bf16 v[96:111], v[226:229], v[238:241], v[96:111]
	ds_read_b64_tr_b16 v[234:235], v245 offset:5120
	ds_read_b64_tr_b16 v[236:237], v245 offset:7168
	ds_read_b64_tr_b16 v[238:239], v245 offset:5632
	ds_read_b64_tr_b16 v[240:241], v245 offset:7680
	s_add_i32 s41, s85, s24
	s_add_i32 m0, s41, 0x8000
	s_nop 0
	global_load_lds_dwordx4 v218, s[2:3] sc1
	s_waitcnt lgkmcnt(8)
	v_mfma_f32_32x32x16_bf16 v[112:127], v[230:233], v[128:131], v[112:127]
	v_mfma_f32_32x32x16_bf16 v[96:111], v[230:233], v[132:135], v[96:111]
	ds_read_b64_tr_b16 v[128:129], v245 offset:16384
	ds_read_b64_tr_b16 v[130:131], v245 offset:18432
	ds_read_b64_tr_b16 v[132:133], v245 offset:16896
	ds_read_b64_tr_b16 v[134:135], v245 offset:18944
	s_add_i32 s41, s85, s24
	s_add_i32 m0, s41, 0xa000
	s_nop 0
	global_load_lds_dwordx4 v217, s[2:3] sc1
	s_waitcnt lgkmcnt(8)
	v_mfma_f32_32x32x16_bf16 v[80:95], v[226:229], v[136:139], v[80:95]
	v_mfma_f32_32x32x16_bf16 v[64:79], v[226:229], v[140:143], v[64:79]
	ds_read_b64_tr_b16 v[136:137], v245 offset:20480
	ds_read_b64_tr_b16 v[138:139], v245 offset:22528
	ds_read_b64_tr_b16 v[140:141], v245 offset:20992
	ds_read_b64_tr_b16 v[142:143], v245 offset:23040
	s_add_i32 s41, s85, s24
	s_add_i32 m0, s41, 0xc000
	s_nop 0
	global_load_lds_dwordx4 v242, s[2:3] sc1
	s_waitcnt lgkmcnt(8)
	v_mfma_f32_32x32x16_bf16 v[80:95], v[230:233], v[234:237], v[80:95]
	v_mfma_f32_32x32x16_bf16 v[64:79], v[230:233], v[238:241], v[64:79]
	ds_read_b64_tr_b16 v[234:235], v245 offset:17408
	ds_read_b64_tr_b16 v[236:237], v245 offset:19456
	ds_read_b64_tr_b16 v[238:239], v245 offset:17920
	ds_read_b64_tr_b16 v[240:241], v245 offset:19968
	s_add_i32 s41, s85, s24
	s_add_i32 m0, s41, 0xe000
	s_nop 0
	global_load_lds_dwordx4 v243, s[2:3] sc1
	s_waitcnt lgkmcnt(8)
	v_mfma_f32_32x32x16_bf16 v[48:63], v[226:229], v[128:131], v[48:63]
	v_mfma_f32_32x32x16_bf16 v[32:47], v[226:229], v[132:135], v[32:47]
	ds_read_b64_tr_b16 v[128:129], v245 offset:21504
	ds_read_b64_tr_b16 v[130:131], v245 offset:23552
	ds_read_b64_tr_b16 v[132:133], v245 offset:22016
	ds_read_b64_tr_b16 v[134:135], v245 offset:24064
	s_mov_b32 m0, s24
	s_nop 0
	global_load_lds_dwordx4 v220, s[86:87] sc1
	s_waitcnt lgkmcnt(8)
	v_mfma_f32_32x32x16_bf16 v[48:63], v[230:233], v[136:139], v[48:63]
	v_mfma_f32_32x32x16_bf16 v[32:47], v[230:233], v[140:143], v[32:47]
	s_add_i32 m0, s24, 0x2000
	s_nop 0
	global_load_lds_dwordx4 v219, s[86:87] sc1
	s_waitcnt lgkmcnt(0)
	v_mfma_f32_32x32x16_bf16 v[16:31], v[226:229], v[234:237], v[16:31]
	v_mfma_f32_32x32x16_bf16 v[0:15], v[226:229], v[238:241], v[0:15]
	v_mfma_f32_32x32x16_bf16 v[16:31], v[230:233], v[128:131], v[16:31]
	v_mfma_f32_32x32x16_bf16 v[0:15], v[230:233], v[132:135], v[0:15]
	s_add_i32 s84, s84, 0x8000
	s_cmp_eq_u32 s84, 0x18000
	s_cselect_b32 s84, 0, s84
	s_add_i32 s25, s25, 1
	s_cmpk_eq_i32 s25, 0x82
	s_cbranch_scc0 .LattnB_m0
	s_waitcnt vmcnt(0)
	s_barrier

; #define SBAR() __builtin_amdgcn_sched_barrier(0)
; #define PVR(S, DA, DB, vbase) do { S[0] = tr_read<v_rd_off(DA, 0, 0)>(vbase); S[1] = tr_read<v_rd_off(DA, 0, 1)>(vbase); S[2] = tr_read<v_rd_off(DB, 0, 0)>(vbase); S[3] = tr_read<v_rd_off(DB, 0, 1)>(vbase); \
;     S[4] = tr_read<v_rd_off(DA, 1, 0)>(vbase); S[5] = tr_read<v_rd_off(DA, 1, 1)>(vbase); S[6] = tr_read<v_rd_off(DB, 1, 0)>(vbase); S[7] = tr_read<v_rd_off(DB, 1, 1)>(vbase); } while (0)
; #define RAWBAR() do { asm volatile("s_waitcnt lgkmcnt(0)" ::: "memory"); __builtin_amdgcn_s_barrier(); asm volatile("" ::: "memory"); } while (0)
; #define RAWBAR() do { asm volatile("s_waitcnt lgkmcnt(0)" ::: "memory"); __builtin_amdgcn_s_barrier(); asm volatile("" ::: "memory"); } while (0)
; #define RAWBAR() do { asm volatile("s_waitcnt lgkmcnt(0)" ::: "memory"); __builtin_amdgcn_s_barrier(); asm volatile("" ::: "memory"); } while (0)
; #define RAWBAR() do { asm volatile("s_waitcnt lgkmcnt(0)" ::: "memory"); __builtin_amdgcn_s_barrier(); asm volatile("" ::: "memory"); } while (0)
; #define RAWBAR() do { asm volatile("s_waitcnt lgkmcnt(0)" ::: "memory"); __builtin_amdgcn_s_barrier(); asm volatile("" ::: "memory"); } while (0)
; template <int MODE> ...
;     ...
;   for (int j = 0; j < NT; ++j) {
;     const int buf = j & 1;
;     if (j + 1 < NT) { STAGE((j + 1) * KVBLK, buf ^ 1); }
;     const char* Kb = K_lds + buf * 16384;
;     f32x16 pe = {}, po = {};
; #pragma unroll
;     for (int d0 = 0; d0 < 8; d0 += 2) {
;       const bf16x8 k0 = *reinterpret_cast<const bf16x8*>(Kb + KSWZ(krow, (d0 * 16 + hi * 8) * 2));
;       const bf16x8 k1 = *reinterpret_cast<const bf16x8*>(Kb + KSWZ(krow, ((d0 + 1) * 16 + hi * 8) * 2));
;       pe = __builtin_amdgcn_mfma_f32_32x32x16_bf16(k0, qr[d0], pe, 0, 0, 0);
;       po = __builtin_amdgcn_mfma_f32_32x32x16_bf16(k1, qr[d0 + 1], po, 0, 0, 0); }
;     const int vo = vb0 + buf * 32768;
;     s16x4 R0_[8], R1_[8];
;     PVR(R0_, 0, 1, vo);
;     f32x16 p;
; #pragma unroll
;     for (int r = 0; r < 16; ++r) p[r] = __builtin_amdgcn_exp2f(fmaf(pe[r] + po[r], C, negMc));
;     float ps = 0.f;
; #pragma unroll
;     for (int r = 0; r < 16; ++r) ps += p[r];
;     lsum += ps;
;     const bf16x8 own0 = pk8(p, 0), own1 = pk8(p, 8);
;     SBAR();
;     PV_TAIL4(o, vo, vo + 16384, own0, own1);
;     asm volatile("s_waitcnt vmcnt(0)" ::: "memory");
;     RAWBAR();
;   }
.LBB0_1023:
	ds_read_b128 v[230:233], v229 offset:16384
	ds_read_b128 v[234:237], v228 offset:16384
	ds_read_b128 v[238:241], v227 offset:16384
	ds_read_b128 v[242:245], v226 offset:16384
	v_exp_f32_e32 v144, v144
	v_exp_f32_e32 v145, v145
	v_exp_f32_e32 v146, v146
	v_exp_f32_e32 v147, v147
	s_waitcnt lgkmcnt(2)
	v_mfma_f32_32x32x16_bf16 v[128:143], v[230:233], v[188:191], 0
	v_mfma_f32_32x32x16_bf16 v[128:143], v[234:237], v[184:187], v[128:143]
	ds_read_b128 v[230:233], v204 offset:16384
	ds_read_b128 v[234:237], v205 offset:16384
	s_mov_b32 m0, s34
	s_nop 0
	global_load_lds_dwordx4 v225, s[86:87] sc1
	s_add_i32 m0, s34, 0x2000
	s_nop 0
	global_load_lds_dwordx4 v223, s[86:87] sc1
	v_exp_f32_e32 v148, v148
	v_exp_f32_e32 v149, v149
	v_exp_f32_e32 v150, v150
	v_exp_f32_e32 v151, v151
	v_add_f32_e32 v250, v144, v145
	v_add_f32_e32 v250, v146, v250
	v_add_f32_e32 v250, v147, v250
	s_waitcnt lgkmcnt(2)
	v_mfma_f32_32x32x16_bf16 v[128:143], v[238:241], v[180:183], v[128:143]
	v_mfma_f32_32x32x16_bf16 v[128:143], v[242:245], v[176:179], v[128:143]
	ds_read_b128 v[238:241], v206 offset:16384
	ds_read_b128 v[242:245], v207 offset:16384
	v_exp_f32_e32 v152, v152
	v_exp_f32_e32 v153, v153
	v_exp_f32_e32 v154, v154
	v_exp_f32_e32 v155, v155
	v_add_f32_e32 v250, v148, v250
	v_add_f32_e32 v250, v149, v250
	v_add_f32_e32 v250, v150, v250
	v_add_f32_e32 v250, v151, v250
	s_waitcnt lgkmcnt(2)
	v_mfma_f32_32x32x16_bf16 v[128:143], v[230:233], v[172:175], v[128:143]
	v_mfma_f32_32x32x16_bf16 v[128:143], v[234:237], v[168:171], v[128:143]
	v_exp_f32_e32 v156, v156
	v_exp_f32_e32 v157, v157
	v_exp_f32_e32 v158, v158
	v_exp_f32_e32 v159, v159
	v_add_f32_e32 v250, v152, v250
	v_add_f32_e32 v250, v153, v250
	v_add_f32_e32 v250, v154, v250
	v_add_f32_e32 v250, v155, v250
	v_cvt_pk_bf16_f32 v230, v144, v145
	v_cvt_pk_bf16_f32 v231, v146, v147
	v_cvt_pk_bf16_f32 v232, v148, v149
	v_cvt_pk_bf16_f32 v233, v150, v151
	s_waitcnt lgkmcnt(0)
	v_mfma_f32_32x32x16_bf16 v[128:143], v[238:241], v[164:167], v[128:143]
	v_mfma_f32_32x32x16_bf16 v[128:143], v[242:245], v[160:163], v[128:143]
	v_add_u32_e32 v249, s84, v218
	s_add_i32 s85, s84, 0x8000
	s_cmp_eq_u32 s85, 0x18000
	s_cselect_b32 s85, 0, s85
	ds_read_b64_tr_b16 v[238:239], v249 offset:0
	ds_read_b64_tr_b16 v[240:241], v249 offset:2048
	ds_read_b64_tr_b16 v[242:243], v249 offset:512
	ds_read_b64_tr_b16 v[244:245], v249 offset:2560
	ds_read_b64_tr_b16 v[144:145], v249 offset:4096
	ds_read_b64_tr_b16 v[146:147], v249 offset:6144
	ds_read_b64_tr_b16 v[148:149], v249 offset:4608
	ds_read_b64_tr_b16 v[150:151], v249 offset:6656
	v_add_f32_e32 v250, v156, v250
	v_add_f32_e32 v250, v157, v250
	v_add_f32_e32 v250, v158, v250
	v_add_f32_e32 v250, v159, v250
	v_cvt_pk_bf16_f32 v234, v152, v153
	v_cvt_pk_bf16_f32 v235, v154, v155
	v_cvt_pk_bf16_f32 v236, v156, v157
	v_cvt_pk_bf16_f32 v237, v158, v159
	v_add_f32_e32 v219, v219, v250
	ds_read_b64_tr_b16 v[152:153], v249 offset:1024
	ds_read_b64_tr_b16 v[154:155], v249 offset:3072
	ds_read_b64_tr_b16 v[156:157], v249 offset:1536
	ds_read_b64_tr_b16 v[158:159], v249 offset:3584
	s_waitcnt lgkmcnt(8)
	v_mfma_f32_32x32x16_bf16 v[112:127], v[230:233], v[238:241], v[112:127]
	v_mfma_f32_32x32x16_bf16 v[96:111], v[230:233], v[242:245], v[96:111]
	ds_read_b64_tr_b16 v[238:239], v249 offset:5120
	ds_read_b64_tr_b16 v[240:241], v249 offset:7168
	ds_read_b64_tr_b16 v[242:243], v249 offset:5632
	ds_read_b64_tr_b16 v[244:245], v249 offset:7680
	s_add_i32 s30, s85, s34
	s_add_i32 m0, s30, 0x8000
	s_nop 0
	global_load_lds_dwordx4 v222, s[2:3] sc1
	s_waitcnt lgkmcnt(8)
	v_mfma_f32_32x32x16_bf16 v[112:127], v[234:237], v[144:147], v[112:127]
	v_mfma_f32_32x32x16_bf16 v[96:111], v[234:237], v[148:151], v[96:111]
	ds_read_b64_tr_b16 v[144:145], v249 offset:16384
	ds_read_b64_tr_b16 v[146:147], v249 offset:18432
	ds_read_b64_tr_b16 v[148:149], v249 offset:16896
	ds_read_b64_tr_b16 v[150:151], v249 offset:18944
	s_add_i32 s30, s85, s34
	s_add_i32 m0, s30, 0xa000
	s_nop 0
	global_load_lds_dwordx4 v221, s[2:3] sc1
	s_waitcnt lgkmcnt(8)
	v_mfma_f32_32x32x16_bf16 v[80:95], v[230:233], v[152:155], v[80:95]
	v_mfma_f32_32x32x16_bf16 v[64:79], v[230:233], v[156:159], v[64:79]
	ds_read_b64_tr_b16 v[152:153], v249 offset:20480
	ds_read_b64_tr_b16 v[154:155], v249 offset:22528
	ds_read_b64_tr_b16 v[156:157], v249 offset:20992
	ds_read_b64_tr_b16 v[158:159], v249 offset:23040
	s_add_i32 s30, s85, s34
	s_add_i32 m0, s30, 0xc000
	s_nop 0
	global_load_lds_dwordx4 v246, s[2:3] sc1
	s_waitcnt lgkmcnt(8)
	v_mfma_f32_32x32x16_bf16 v[80:95], v[234:237], v[238:241], v[80:95]
	v_mfma_f32_32x32x16_bf16 v[64:79], v[234:237], v[242:245], v[64:79]
	ds_read_b64_tr_b16 v[238:239], v249 offset:17408
	ds_read_b64_tr_b16 v[240:241], v249 offset:19456
	ds_read_b64_tr_b16 v[242:243], v249 offset:17920
	ds_read_b64_tr_b16 v[244:245], v249 offset:19968
	s_add_i32 s30, s85, s34
	s_add_i32 m0, s30, 0xe000
	s_nop 0
	global_load_lds_dwordx4 v247, s[2:3] sc1
	s_waitcnt lgkmcnt(8)
	v_mfma_f32_32x32x16_bf16 v[32:47], v[230:233], v[144:147], v[32:47]
	v_mfma_f32_32x32x16_bf16 v[16:31], v[230:233], v[148:151], v[16:31]
	ds_read_b64_tr_b16 v[144:145], v249 offset:21504
	ds_read_b64_tr_b16 v[146:147], v249 offset:23552
	ds_read_b64_tr_b16 v[148:149], v249 offset:22016
	ds_read_b64_tr_b16 v[150:151], v249 offset:24064
	s_waitcnt lgkmcnt(8)
	v_mfma_f32_32x32x16_bf16 v[32:47], v[234:237], v[152:155], v[32:47]
	v_mfma_f32_32x32x16_bf16 v[16:31], v[234:237], v[156:159], v[16:31]
	s_waitcnt lgkmcnt(0)
	v_mfma_f32_32x32x16_bf16 v[48:63], v[230:233], v[238:241], v[48:63]
	s_waitcnt vmcnt(0)
	s_barrier
; #define SBAR() __builtin_amdgcn_sched_barrier(0)
; #define PVR(S, DA, DB, vbase) do { S[0] = tr_read<v_rd_off(DA, 0, 0)>(vbase); S[1] = tr_read<v_rd_off(DA, 0, 1)>(vbase); S[2] = tr_read<v_rd_off(DB, 0, 0)>(vbase); S[3] = tr_read<v_rd_off(DB, 0, 1)>(vbase); \
;     S[4] = tr_read<v_rd_off(DA, 1, 0)>(vbase); S[5] = tr_read<v_rd_off(DA, 1, 1)>(vbase); S[6] = tr_read<v_rd_off(DB, 1, 0)>(vbase); S[7] = tr_read<v_rd_off(DB, 1, 1)>(vbase); } while (0)
; #define RAWBAR() do { asm volatile("s_waitcnt lgkmcnt(0)" ::: "memory"); __builtin_amdgcn_s_barrier(); asm volatile("" ::: "memory"); } while (0)
; #define RAWBAR() do { asm volatile("s_waitcnt lgkmcnt(0)" ::: "memory"); __builtin_amdgcn_s_barrier(); asm volatile("" ::: "memory"); } while (0)
; #define RAWBAR() do { asm volatile("s_waitcnt lgkmcnt(0)" ::: "memory"); __builtin_amdgcn_s_barrier(); asm volatile("" ::: "memory"); } while (0)
; #define RAWBAR() do { asm volatile("s_waitcnt lgkmcnt(0)" ::: "memory"); __builtin_amdgcn_s_barrier(); asm volatile("" ::: "memory"); } while (0)
; #define RAWBAR() do { asm volatile("s_waitcnt lgkmcnt(0)" ::: "memory"); __builtin_amdgcn_s_barrier(); asm volatile("" ::: "memory"); } while (0)
; template <int MODE> ...
;     ...
;   for (int j = 0; j < NT; ++j) {
;     const int buf = j & 1;
;     if (j + 1 < NT) { STAGE((j + 1) * KVBLK, buf ^ 1); }
;     const char* Kb = K_lds + buf * 16384;
;     f32x16 pe = {}, po = {};
; #pragma unroll
;     for (int d0 = 0; d0 < 8; d0 += 2) {
;       const bf16x8 k0 = *reinterpret_cast<const bf16x8*>(Kb + KSWZ(krow, (d0 * 16 + hi * 8) * 2));
;       const bf16x8 k1 = *reinterpret_cast<const bf16x8*>(Kb + KSWZ(krow, ((d0 + 1) * 16 + hi * 8) * 2));
;       pe = __builtin_amdgcn_mfma_f32_32x32x16_bf16(k0, qr[d0], pe, 0, 0, 0);
;       po = __builtin_amdgcn_mfma_f32_32x32x16_bf16(k1, qr[d0 + 1], po, 0, 0, 0); }
;     const int vo = vb0 + buf * 32768;
;     s16x4 R0_[8], R1_[8];
;     PVR(R0_, 0, 1, vo);
;     f32x16 p;
; #pragma unroll
;     for (int r = 0; r < 16; ++r) p[r] = __builtin_amdgcn_exp2f(fmaf(pe[r] + po[r], C, negMc));
;     float ps = 0.f;
; #pragma unroll
;     for (int r = 0; r < 16; ++r) ps += p[r];
;     lsum += ps;
;     const bf16x8 own0 = pk8(p, 0), own1 = pk8(p, 8);
;     SBAR();
;     PV_TAIL4(o, vo, vo + 16384, own0, own1);
;     asm volatile("s_waitcnt vmcnt(0)" ::: "memory");
;     RAWBAR();
;   }
	s_add_u32 s86, s86, 0x4000
	s_addc_u32 s87, s87, 0
	s_add_u32 s2, s2, 0x8000
	s_addc_u32 s3, s3, 0
	v_mfma_f32_32x32x16_bf16 v[0:15], v[230:233], v[242:245], v[0:15]
	v_mfma_f32_32x32x16_bf16 v[48:63], v[234:237], v[144:147], v[48:63]
	v_mfma_f32_32x32x16_bf16 v[0:15], v[234:237], v[148:151], v[0:15]
	s_add_i32 s84, s84, 0x8000
	s_cmp_eq_u32 s84, 0x18000
	s_cselect_b32 s84, 0, s84
	ds_read_b128 v[230:233], v229 offset:0
	ds_read_b128 v[234:237], v228 offset:0
	ds_read_b128 v[238:241], v227 offset:0
	ds_read_b128 v[242:245], v226 offset:0
	v_exp_f32_e32 v128, v128
	v_exp_f32_e32 v129, v129
	v_exp_f32_e32 v130, v130
	v_exp_f32_e32 v131, v131
	s_waitcnt lgkmcnt(2)
	v_mfma_f32_32x32x16_bf16 v[144:159], v[230:233], v[188:191], 0
	v_mfma_f32_32x32x16_bf16 v[144:159], v[234:237], v[184:187], v[144:159]
	ds_read_b128 v[230:233], v204 offset:0
	ds_read_b128 v[234:237], v205 offset:0
	s_add_i32 m0, s34, 0x4000
	s_nop 0
	global_load_lds_dwordx4 v225, s[86:87] sc1
	s_add_i32 m0, s34, 0x6000
	s_nop 0
	global_load_lds_dwordx4 v223, s[86:87] sc1
	v_exp_f32_e32 v132, v132
	v_exp_f32_e32 v133, v133
	v_exp_f32_e32 v134, v134
	v_exp_f32_e32 v135, v135
	v_add_f32_e32 v250, v128, v129
	v_add_f32_e32 v250, v130, v250
	v_add_f32_e32 v250, v131, v250
	s_waitcnt lgkmcnt(2)
	v_mfma_f32_32x32x16_bf16 v[144:159], v[238:241], v[180:183], v[144:159]
	v_mfma_f32_32x32x16_bf16 v[144:159], v[242:245], v[176:179], v[144:159]
	ds_read_b128 v[238:241], v206 offset:0
	ds_read_b128 v[242:245], v207 offset:0
	v_exp_f32_e32 v136, v136
	v_exp_f32_e32 v137, v137
	v_exp_f32_e32 v138, v138
	v_exp_f32_e32 v139, v139
	v_add_f32_e32 v250, v132, v250
	v_add_f32_e32 v250, v133, v250
	v_add_f32_e32 v250, v134, v250
	v_add_f32_e32 v250, v135, v250
	s_waitcnt lgkmcnt(2)
	v_mfma_f32_32x32x16_bf16 v[144:159], v[230:233], v[172:175], v[144:159]
	v_mfma_f32_32x32x16_bf16 v[144:159], v[234:237], v[168:171], v[144:159]
	v_exp_f32_e32 v140, v140
	v_exp_f32_e32 v141, v141
	v_exp_f32_e32 v142, v142
	v_exp_f32_e32 v143, v143
	v_add_f32_e32 v250, v136, v250
	v_add_f32_e32 v250, v137, v250
	v_add_f32_e32 v250, v138, v250
	v_add_f32_e32 v250, v139, v250
	v_cvt_pk_bf16_f32 v230, v128, v129
	v_cvt_pk_bf16_f32 v231, v130, v131
	v_cvt_pk_bf16_f32 v232, v132, v133
	v_cvt_pk_bf16_f32 v233, v134, v135
	s_waitcnt lgkmcnt(0)
	v_mfma_f32_32x32x16_bf16 v[144:159], v[238:241], v[164:167], v[144:159]
	v_mfma_f32_32x32x16_bf16 v[144:159], v[242:245], v[160:163], v[144:159]
	v_add_u32_e32 v249, s84, v218
	s_add_i32 s85, s84, 0x8000
	s_cmp_eq_u32 s85, 0x18000
	s_cselect_b32 s85, 0, s85
	ds_read_b64_tr_b16 v[238:239], v249 offset:0
	ds_read_b64_tr_b16 v[240:241], v249 offset:2048
	ds_read_b64_tr_b16 v[242:243], v249 offset:512
	ds_read_b64_tr_b16 v[244:245], v249 offset:2560
	ds_read_b64_tr_b16 v[128:129], v249 offset:4096
	ds_read_b64_tr_b16 v[130:131], v249 offset:6144
	ds_read_b64_tr_b16 v[132:133], v249 offset:4608
	ds_read_b64_tr_b16 v[134:135], v249 offset:6656
	v_add_f32_e32 v250, v140, v250
	v_add_f32_e32 v250, v141, v250
	v_add_f32_e32 v250, v142, v250
	v_add_f32_e32 v250, v143, v250
	v_cvt_pk_bf16_f32 v234, v136, v137
	v_cvt_pk_bf16_f32 v235, v138, v139
	v_cvt_pk_bf16_f32 v236, v140, v141
	v_cvt_pk_bf16_f32 v237, v142, v143
	v_add_f32_e32 v219, v219, v250
	ds_read_b64_tr_b16 v[136:137], v249 offset:1024
	ds_read_b64_tr_b16 v[138:139], v249 offset:3072
	ds_read_b64_tr_b16 v[140:141], v249 offset:1536
	ds_read_b64_tr_b16 v[142:143], v249 offset:3584
	s_waitcnt lgkmcnt(8)
	v_mfma_f32_32x32x16_bf16 v[112:127], v[230:233], v[238:241], v[112:127]
	v_mfma_f32_32x32x16_bf16 v[96:111], v[230:233], v[242:245], v[96:111]
	ds_read_b64_tr_b16 v[238:239], v249 offset:5120
	ds_read_b64_tr_b16 v[240:241], v249 offset:7168
	ds_read_b64_tr_b16 v[242:243], v249 offset:5632
	ds_read_b64_tr_b16 v[244:245], v249 offset:7680
	s_add_i32 s30, s85, s34
	s_add_i32 m0, s30, 0x8000
	s_nop 0
	global_load_lds_dwordx4 v222, s[2:3] sc1
	s_waitcnt lgkmcnt(8)
	v_mfma_f32_32x32x16_bf16 v[112:127], v[234:237], v[128:131], v[112:127]
	v_mfma_f32_32x32x16_bf16 v[96:111], v[234:237], v[132:135], v[96:111]
	ds_read_b64_tr_b16 v[128:129], v249 offset:16384
	ds_read_b64_tr_b16 v[130:131], v249 offset:18432
	ds_read_b64_tr_b16 v[132:133], v249 offset:16896
	ds_read_b64_tr_b16 v[134:135], v249 offset:18944
	s_add_i32 s30, s85, s34
	s_add_i32 m0, s30, 0xa000
	s_nop 0
	global_load_lds_dwordx4 v221, s[2:3] sc1
	s_waitcnt lgkmcnt(8)
	v_mfma_f32_32x32x16_bf16 v[80:95], v[230:233], v[136:139], v[80:95]
	v_mfma_f32_32x32x16_bf16 v[64:79], v[230:233], v[140:143], v[64:79]
	ds_read_b64_tr_b16 v[136:137], v249 offset:20480
	ds_read_b64_tr_b16 v[138:139], v249 offset:22528
	ds_read_b64_tr_b16 v[140:141], v249 offset:20992
	ds_read_b64_tr_b16 v[142:143], v249 offset:23040
	s_add_i32 s30, s85, s34
	s_add_i32 m0, s30, 0xc000
	s_nop 0
	global_load_lds_dwordx4 v246, s[2:3] sc1
	s_waitcnt lgkmcnt(8)
	v_mfma_f32_32x32x16_bf16 v[80:95], v[234:237], v[238:241], v[80:95]
	v_mfma_f32_32x32x16_bf16 v[64:79], v[234:237], v[242:245], v[64:79]
	ds_read_b64_tr_b16 v[238:239], v249 offset:17408
	ds_read_b64_tr_b16 v[240:241], v249 offset:19456
	ds_read_b64_tr_b16 v[242:243], v249 offset:17920
	ds_read_b64_tr_b16 v[244:245], v249 offset:19968
	s_add_i32 s30, s85, s34
	s_add_i32 m0, s30, 0xe000
	s_nop 0
	global_load_lds_dwordx4 v247, s[2:3] sc1
	s_waitcnt lgkmcnt(8)
	v_mfma_f32_32x32x16_bf16 v[32:47], v[230:233], v[128:131], v[32:47]
	v_mfma_f32_32x32x16_bf16 v[16:31], v[230:233], v[132:135], v[16:31]
	ds_read_b64_tr_b16 v[128:129], v249 offset:21504
	ds_read_b64_tr_b16 v[130:131], v249 offset:23552
	ds_read_b64_tr_b16 v[132:133], v249 offset:22016
	ds_read_b64_tr_b16 v[134:135], v249 offset:24064
	s_waitcnt lgkmcnt(8)
	v_mfma_f32_32x32x16_bf16 v[32:47], v[234:237], v[136:139], v[32:47]
	v_mfma_f32_32x32x16_bf16 v[16:31], v[234:237], v[140:143], v[16:31]
	s_waitcnt lgkmcnt(0)
	v_mfma_f32_32x32x16_bf16 v[48:63], v[230:233], v[238:241], v[48:63]
	s_waitcnt vmcnt(0)
	s_barrier
	s_add_u32 s86, s86, 0x4000
	s_addc_u32 s87, s87, 0
	s_add_u32 s2, s2, 0x8000
	s_addc_u32 s3, s3, 0
	v_mfma_f32_32x32x16_bf16 v[0:15], v[230:233], v[242:245], v[0:15]
	v_mfma_f32_32x32x16_bf16 v[48:63], v[234:237], v[128:131], v[48:63]
	v_mfma_f32_32x32x16_bf16 v[0:15], v[234:237], v[132:135], v[0:15]
	s_add_i32 s84, s84, 0x8000
	s_cmp_eq_u32 s84, 0x18000
	s_cselect_b32 s84, 0, s84
	s_add_i32 s40, s40, 1
	s_cmpk_eq_i32 s40, 0x82
	s_cbranch_scc0 .LBB0_1023
	s_barrier
	s_branch .Lattn_join_m1

; #define SBAR() __builtin_amdgcn_sched_barrier(0)
; #define PVR(S, DA, DB, vbase) do { S[0] = tr_read<v_rd_off(DA, 0, 0)>(vbase); S[1] = tr_read<v_rd_off(DA, 0, 1)>(vbase); S[2] = tr_read<v_rd_off(DB, 0, 0)>(vbase); S[3] = tr_read<v_rd_off(DB, 0, 1)>(vbase); \
;     S[4] = tr_read<v_rd_off(DA, 1, 0)>(vbase); S[5] = tr_read<v_rd_off(DA, 1, 1)>(vbase); S[6] = tr_read<v_rd_off(DB, 1, 0)>(vbase); S[7] = tr_read<v_rd_off(DB, 1, 1)>(vbase); } while (0)
; #define RAWBAR() do { asm volatile("s_waitcnt lgkmcnt(0)" ::: "memory"); __builtin_amdgcn_s_barrier(); asm volatile("" ::: "memory"); } while (0)
; #define RAWBAR() do { asm volatile("s_waitcnt lgkmcnt(0)" ::: "memory"); __builtin_amdgcn_s_barrier(); asm volatile("" ::: "memory"); } while (0)
; #define RAWBAR() do { asm volatile("s_waitcnt lgkmcnt(0)" ::: "memory"); __builtin_amdgcn_s_barrier(); asm volatile("" ::: "memory"); } while (0)
; #define RAWBAR() do { asm volatile("s_waitcnt lgkmcnt(0)" ::: "memory"); __builtin_amdgcn_s_barrier(); asm volatile("" ::: "memory"); } while (0)
; #define RAWBAR() do { asm volatile("s_waitcnt lgkmcnt(0)" ::: "memory"); __builtin_amdgcn_s_barrier(); asm volatile("" ::: "memory"); } while (0)
; template <int MODE> ...
;     ...
;   for (int j = 0; j < NT; ++j) {
;     const int buf = j & 1;
;     if (j + 1 < NT) { STAGE((j + 1) * KVBLK, buf ^ 1); }
;     const char* Kb = K_lds + buf * 16384;
;     f32x16 pe = {}, po = {};
; #pragma unroll
;     for (int d0 = 0; d0 < 8; d0 += 2) {
;       const bf16x8 k0 = *reinterpret_cast<const bf16x8*>(Kb + KSWZ(krow, (d0 * 16 + hi * 8) * 2));
;       const bf16x8 k1 = *reinterpret_cast<const bf16x8*>(Kb + KSWZ(krow, ((d0 + 1) * 16 + hi * 8) * 2));
;       pe = __builtin_amdgcn_mfma_f32_32x32x16_bf16(k0, qr[d0], pe, 0, 0, 0);
;       po = __builtin_amdgcn_mfma_f32_32x32x16_bf16(k1, qr[d0 + 1], po, 0, 0, 0); }
;     const int vo = vb0 + buf * 32768;
;     s16x4 R0_[8], R1_[8];
;     PVR(R0_, 0, 1, vo);
;     f32x16 p;
; #pragma unroll
;     for (int r = 0; r < 16; ++r) p[r] = __builtin_amdgcn_exp2f(fmaf(pe[r] + po[r], C, negMc));
;     float ps = 0.f;
; #pragma unroll
;     for (int r = 0; r < 16; ++r) ps += p[r];
;     lsum += ps;
;     const bf16x8 own0 = pk8(p, 0), own1 = pk8(p, 8);
;     SBAR();
;     PV_TAIL4(o, vo, vo + 16384, own0, own1);
;     asm volatile("s_waitcnt vmcnt(0)" ::: "memory");
;     RAWBAR();
;   }
.LattnB_m1:
	ds_read_b128 v[230:233], v229 offset:16384
	ds_read_b128 v[234:237], v228 offset:16384
	ds_read_b128 v[238:241], v227 offset:16384
	ds_read_b128 v[242:245], v226 offset:16384
	v_exp_f32_e32 v144, v144
	v_exp_f32_e32 v145, v145
	v_exp_f32_e32 v146, v146
	v_exp_f32_e32 v147, v147
	s_waitcnt lgkmcnt(2)
	v_mfma_f32_32x32x16_bf16 v[128:143], v[230:233], v[188:191], 0
	v_mfma_f32_32x32x16_bf16 v[128:143], v[234:237], v[184:187], v[128:143]
	ds_read_b128 v[230:233], v204 offset:16384
	ds_read_b128 v[234:237], v205 offset:16384
	v_exp_f32_e32 v148, v148
	v_exp_f32_e32 v149, v149
	v_exp_f32_e32 v150, v150
	v_exp_f32_e32 v151, v151
	v_add_f32_e32 v250, v144, v145
	v_add_f32_e32 v250, v146, v250
	v_add_f32_e32 v250, v147, v250
	s_waitcnt lgkmcnt(2)
	v_mfma_f32_32x32x16_bf16 v[128:143], v[238:241], v[180:183], v[128:143]
	v_mfma_f32_32x32x16_bf16 v[128:143], v[242:245], v[176:179], v[128:143]
	ds_read_b128 v[238:241], v206 offset:16384
	ds_read_b128 v[242:245], v207 offset:16384
	v_exp_f32_e32 v152, v152
	v_exp_f32_e32 v153, v153
	v_exp_f32_e32 v154, v154
	v_exp_f32_e32 v155, v155
	v_add_f32_e32 v250, v148, v250
	v_add_f32_e32 v250, v149, v250
	v_add_f32_e32 v250, v150, v250
	v_add_f32_e32 v250, v151, v250
	s_waitcnt lgkmcnt(2)
	v_mfma_f32_32x32x16_bf16 v[128:143], v[230:233], v[172:175], v[128:143]
	v_mfma_f32_32x32x16_bf16 v[128:143], v[234:237], v[168:171], v[128:143]
	v_exp_f32_e32 v156, v156
	v_exp_f32_e32 v157, v157
	v_exp_f32_e32 v158, v158
	v_exp_f32_e32 v159, v159
	v_add_f32_e32 v250, v152, v250
	v_add_f32_e32 v250, v153, v250
	v_add_f32_e32 v250, v154, v250
	v_add_f32_e32 v250, v155, v250
	v_cvt_pk_bf16_f32 v230, v144, v145
	v_cvt_pk_bf16_f32 v231, v146, v147
	v_cvt_pk_bf16_f32 v232, v148, v149
	v_cvt_pk_bf16_f32 v233, v150, v151
	s_waitcnt lgkmcnt(0)
	v_mfma_f32_32x32x16_bf16 v[128:143], v[238:241], v[164:167], v[128:143]
	v_mfma_f32_32x32x16_bf16 v[128:143], v[242:245], v[160:163], v[128:143]
	s_waitcnt vmcnt(0)
	s_barrier
	s_add_u32 s86, s86, 0x4000
	s_addc_u32 s87, s87, 0
	s_add_u32 s2, s2, 0x8000
	s_addc_u32 s3, s3, 0
	v_add_u32_e32 v249, s84, v218
	s_sub_u32 s85, s84, 0x8000
	s_cmp_eq_u32 s84, 0
	s_cselect_b32 s85, 0x10000, s85
	ds_read_b64_tr_b16 v[238:239], v249 offset:0
	ds_read_b64_tr_b16 v[240:241], v249 offset:2048
	ds_read_b64_tr_b16 v[242:243], v249 offset:512
	ds_read_b64_tr_b16 v[244:245], v249 offset:2560
	ds_read_b64_tr_b16 v[144:145], v249 offset:4096
	ds_read_b64_tr_b16 v[146:147], v249 offset:6144
	ds_read_b64_tr_b16 v[148:149], v249 offset:4608
	ds_read_b64_tr_b16 v[150:151], v249 offset:6656
	v_add_f32_e32 v250, v156, v250
	v_add_f32_e32 v250, v157, v250
	v_add_f32_e32 v250, v158, v250
	v_add_f32_e32 v250, v159, v250
	v_cvt_pk_bf16_f32 v234, v152, v153
	v_cvt_pk_bf16_f32 v235, v154, v155
	v_cvt_pk_bf16_f32 v236, v156, v157
	v_cvt_pk_bf16_f32 v237, v158, v159
	v_add_f32_e32 v219, v219, v250
	ds_read_b64_tr_b16 v[152:153], v249 offset:1024
	ds_read_b64_tr_b16 v[154:155], v249 offset:3072
	ds_read_b64_tr_b16 v[156:157], v249 offset:1536
	ds_read_b64_tr_b16 v[158:159], v249 offset:3584
	s_waitcnt lgkmcnt(8)
	v_mfma_f32_32x32x16_bf16 v[112:127], v[230:233], v[238:241], v[112:127]
	v_mfma_f32_32x32x16_bf16 v[96:111], v[230:233], v[242:245], v[96:111]
	ds_read_b64_tr_b16 v[238:239], v249 offset:5120
	ds_read_b64_tr_b16 v[240:241], v249 offset:7168
	ds_read_b64_tr_b16 v[242:243], v249 offset:5632
	ds_read_b64_tr_b16 v[244:245], v249 offset:7680
	s_add_i32 s30, s85, s34
	s_add_i32 m0, s30, 0x8000
	s_nop 0
	global_load_lds_dwordx4 v222, s[2:3] sc1
	s_waitcnt lgkmcnt(8)
	v_mfma_f32_32x32x16_bf16 v[112:127], v[234:237], v[144:147], v[112:127]
	v_mfma_f32_32x32x16_bf16 v[96:111], v[234:237], v[148:151], v[96:111]
	ds_read_b64_tr_b16 v[144:145], v249 offset:16384
	ds_read_b64_tr_b16 v[146:147], v249 offset:18432
	ds_read_b64_tr_b16 v[148:149], v249 offset:16896
	ds_read_b64_tr_b16 v[150:151], v249 offset:18944
	s_add_i32 s30, s85, s34
	s_add_i32 m0, s30, 0xa000
	s_nop 0
	global_load_lds_dwordx4 v221, s[2:3] sc1
	s_waitcnt lgkmcnt(8)
	v_mfma_f32_32x32x16_bf16 v[80:95], v[230:233], v[152:155], v[80:95]
	v_mfma_f32_32x32x16_bf16 v[64:79], v[230:233], v[156:159], v[64:79]
	ds_read_b64_tr_b16 v[152:153], v249 offset:20480
	ds_read_b64_tr_b16 v[154:155], v249 offset:22528
	ds_read_b64_tr_b16 v[156:157], v249 offset:20992
	ds_read_b64_tr_b16 v[158:159], v249 offset:23040
	s_add_i32 s30, s85, s34
	s_add_i32 m0, s30, 0xc000
	s_nop 0
	global_load_lds_dwordx4 v246, s[2:3] sc1
	s_waitcnt lgkmcnt(8)
	v_mfma_f32_32x32x16_bf16 v[80:95], v[234:237], v[238:241], v[80:95]
	v_mfma_f32_32x32x16_bf16 v[64:79], v[234:237], v[242:245], v[64:79]
	ds_read_b64_tr_b16 v[238:239], v249 offset:17408
	ds_read_b64_tr_b16 v[240:241], v249 offset:19456
	ds_read_b64_tr_b16 v[242:243], v249 offset:17920
	ds_read_b64_tr_b16 v[244:245], v249 offset:19968
	s_add_i32 s30, s85, s34
	s_add_i32 m0, s30, 0xe000
	s_nop 0
	global_load_lds_dwordx4 v247, s[2:3] sc1
	s_waitcnt lgkmcnt(8)
	v_mfma_f32_32x32x16_bf16 v[32:47], v[230:233], v[144:147], v[32:47]
	v_mfma_f32_32x32x16_bf16 v[16:31], v[230:233], v[148:151], v[16:31]
	ds_read_b64_tr_b16 v[144:145], v249 offset:21504
	ds_read_b64_tr_b16 v[146:147], v249 offset:23552
	ds_read_b64_tr_b16 v[148:149], v249 offset:22016
	ds_read_b64_tr_b16 v[150:151], v249 offset:24064
	s_add_i32 m0, s34, 0x4000
	s_nop 0
	global_load_lds_dwordx4 v225, s[86:87] sc1
	s_waitcnt lgkmcnt(8)
	v_mfma_f32_32x32x16_bf16 v[32:47], v[234:237], v[152:155], v[32:47]
	v_mfma_f32_32x32x16_bf16 v[16:31], v[234:237], v[156:159], v[16:31]
	s_add_i32 m0, s34, 0x6000
	s_nop 0
	global_load_lds_dwordx4 v223, s[86:87] sc1
	s_waitcnt lgkmcnt(0)
; #define SBAR() __builtin_amdgcn_sched_barrier(0)
; #define PVR(S, DA, DB, vbase) do { S[0] = tr_read<v_rd_off(DA, 0, 0)>(vbase); S[1] = tr_read<v_rd_off(DA, 0, 1)>(vbase); S[2] = tr_read<v_rd_off(DB, 0, 0)>(vbase); S[3] = tr_read<v_rd_off(DB, 0, 1)>(vbase); \
;     S[4] = tr_read<v_rd_off(DA, 1, 0)>(vbase); S[5] = tr_read<v_rd_off(DA, 1, 1)>(vbase); S[6] = tr_read<v_rd_off(DB, 1, 0)>(vbase); S[7] = tr_read<v_rd_off(DB, 1, 1)>(vbase); } while (0)
; #define RAWBAR() do { asm volatile("s_waitcnt lgkmcnt(0)" ::: "memory"); __builtin_amdgcn_s_barrier(); asm volatile("" ::: "memory"); } while (0)
; #define RAWBAR() do { asm volatile("s_waitcnt lgkmcnt(0)" ::: "memory"); __builtin_amdgcn_s_barrier(); asm volatile("" ::: "memory"); } while (0)
; #define RAWBAR() do { asm volatile("s_waitcnt lgkmcnt(0)" ::: "memory"); __builtin_amdgcn_s_barrier(); asm volatile("" ::: "memory"); } while (0)
; #define RAWBAR() do { asm volatile("s_waitcnt lgkmcnt(0)" ::: "memory"); __builtin_amdgcn_s_barrier(); asm volatile("" ::: "memory"); } while (0)
; #define RAWBAR() do { asm volatile("s_waitcnt lgkmcnt(0)" ::: "memory"); __builtin_amdgcn_s_barrier(); asm volatile("" ::: "memory"); } while (0)
; template <int MODE> ...
;     ...
;   for (int j = 0; j < NT; ++j) {
;     const int buf = j & 1;
;     if (j + 1 < NT) { STAGE((j + 1) * KVBLK, buf ^ 1); }
;     const char* Kb = K_lds + buf * 16384;
;     f32x16 pe = {}, po = {};
; #pragma unroll
;     for (int d0 = 0; d0 < 8; d0 += 2) {
;       const bf16x8 k0 = *reinterpret_cast<const bf16x8*>(Kb + KSWZ(krow, (d0 * 16 + hi * 8) * 2));
;       const bf16x8 k1 = *reinterpret_cast<const bf16x8*>(Kb + KSWZ(krow, ((d0 + 1) * 16 + hi * 8) * 2));
;       pe = __builtin_amdgcn_mfma_f32_32x32x16_bf16(k0, qr[d0], pe, 0, 0, 0);
;       po = __builtin_amdgcn_mfma_f32_32x32x16_bf16(k1, qr[d0 + 1], po, 0, 0, 0); }
;     const int vo = vb0 + buf * 32768;
;     s16x4 R0_[8], R1_[8];
;     PVR(R0_, 0, 1, vo);
;     f32x16 p;
; #pragma unroll
;     for (int r = 0; r < 16; ++r) p[r] = __builtin_amdgcn_exp2f(fmaf(pe[r] + po[r], C, negMc));
;     float ps = 0.f;
; #pragma unroll
;     for (int r = 0; r < 16; ++r) ps += p[r];
;     lsum += ps;
;     const bf16x8 own0 = pk8(p, 0), own1 = pk8(p, 8);
;     SBAR();
;     PV_TAIL4(o, vo, vo + 16384, own0, own1);
;     asm volatile("s_waitcnt vmcnt(0)" ::: "memory");
;     RAWBAR();
;   }
	v_mfma_f32_32x32x16_bf16 v[48:63], v[230:233], v[238:241], v[48:63]
	v_mfma_f32_32x32x16_bf16 v[0:15], v[230:233], v[242:245], v[0:15]
	v_mfma_f32_32x32x16_bf16 v[48:63], v[234:237], v[144:147], v[48:63]
	v_mfma_f32_32x32x16_bf16 v[0:15], v[234:237], v[148:151], v[0:15]
	s_add_i32 s84, s84, 0x8000
	s_cmp_eq_u32 s84, 0x18000
	s_cselect_b32 s84, 0, s84
	ds_read_b128 v[230:233], v229 offset:0
	ds_read_b128 v[234:237], v228 offset:0
	ds_read_b128 v[238:241], v227 offset:0
	ds_read_b128 v[242:245], v226 offset:0
	v_exp_f32_e32 v128, v128
	v_exp_f32_e32 v129, v129
	v_exp_f32_e32 v130, v130
	v_exp_f32_e32 v131, v131
	s_waitcnt lgkmcnt(2)
	v_mfma_f32_32x32x16_bf16 v[144:159], v[230:233], v[188:191], 0
	v_mfma_f32_32x32x16_bf16 v[144:159], v[234:237], v[184:187], v[144:159]
	ds_read_b128 v[230:233], v204 offset:0
	ds_read_b128 v[234:237], v205 offset:0
	v_exp_f32_e32 v132, v132
	v_exp_f32_e32 v133, v133
	v_exp_f32_e32 v134, v134
	v_exp_f32_e32 v135, v135
	v_add_f32_e32 v250, v128, v129
	v_add_f32_e32 v250, v130, v250
	v_add_f32_e32 v250, v131, v250
	s_waitcnt lgkmcnt(2)
	v_mfma_f32_32x32x16_bf16 v[144:159], v[238:241], v[180:183], v[144:159]
	v_mfma_f32_32x32x16_bf16 v[144:159], v[242:245], v[176:179], v[144:159]
	ds_read_b128 v[238:241], v206 offset:0
	ds_read_b128 v[242:245], v207 offset:0
	v_exp_f32_e32 v136, v136
	v_exp_f32_e32 v137, v137
	v_exp_f32_e32 v138, v138
	v_exp_f32_e32 v139, v139
	v_add_f32_e32 v250, v132, v250
	v_add_f32_e32 v250, v133, v250
	v_add_f32_e32 v250, v134, v250
	v_add_f32_e32 v250, v135, v250
	s_waitcnt lgkmcnt(2)
	v_mfma_f32_32x32x16_bf16 v[144:159], v[230:233], v[172:175], v[144:159]
	v_mfma_f32_32x32x16_bf16 v[144:159], v[234:237], v[168:171], v[144:159]
	v_exp_f32_e32 v140, v140
	v_exp_f32_e32 v141, v141
	v_exp_f32_e32 v142, v142
	v_exp_f32_e32 v143, v143
	v_add_f32_e32 v250, v136, v250
	v_add_f32_e32 v250, v137, v250
	v_add_f32_e32 v250, v138, v250
	v_add_f32_e32 v250, v139, v250
	v_cvt_pk_bf16_f32 v230, v128, v129
	v_cvt_pk_bf16_f32 v231, v130, v131
	v_cvt_pk_bf16_f32 v232, v132, v133
	v_cvt_pk_bf16_f32 v233, v134, v135
	s_waitcnt lgkmcnt(0)
	v_mfma_f32_32x32x16_bf16 v[144:159], v[238:241], v[164:167], v[144:159]
	v_mfma_f32_32x32x16_bf16 v[144:159], v[242:245], v[160:163], v[144:159]
	s_waitcnt vmcnt(0)
	s_barrier
	s_add_u32 s86, s86, 0x4000
	s_addc_u32 s87, s87, 0
	s_add_u32 s2, s2, 0x8000
	s_addc_u32 s3, s3, 0
	v_add_u32_e32 v249, s84, v218
	s_sub_u32 s85, s84, 0x8000
	s_cmp_eq_u32 s84, 0
	s_cselect_b32 s85, 0x10000, s85
	ds_read_b64_tr_b16 v[238:239], v249 offset:0
	ds_read_b64_tr_b16 v[240:241], v249 offset:2048
	ds_read_b64_tr_b16 v[242:243], v249 offset:512
	ds_read_b64_tr_b16 v[244:245], v249 offset:2560
	ds_read_b64_tr_b16 v[128:129], v249 offset:4096
	ds_read_b64_tr_b16 v[130:131], v249 offset:6144
	ds_read_b64_tr_b16 v[132:133], v249 offset:4608
	ds_read_b64_tr_b16 v[134:135], v249 offset:6656
	v_add_f32_e32 v250, v140, v250
	v_add_f32_e32 v250, v141, v250
	v_add_f32_e32 v250, v142, v250
	v_add_f32_e32 v250, v143, v250
	v_cvt_pk_bf16_f32 v234, v136, v137
	v_cvt_pk_bf16_f32 v235, v138, v139
	v_cvt_pk_bf16_f32 v236, v140, v141
	v_cvt_pk_bf16_f32 v237, v142, v143
	v_add_f32_e32 v219, v219, v250
	ds_read_b64_tr_b16 v[136:137], v249 offset:1024
	ds_read_b64_tr_b16 v[138:139], v249 offset:3072
	ds_read_b64_tr_b16 v[140:141], v249 offset:1536
	ds_read_b64_tr_b16 v[142:143], v249 offset:3584
	s_waitcnt lgkmcnt(8)
	v_mfma_f32_32x32x16_bf16 v[112:127], v[230:233], v[238:241], v[112:127]
	v_mfma_f32_32x32x16_bf16 v[96:111], v[230:233], v[242:245], v[96:111]
	ds_read_b64_tr_b16 v[238:239], v249 offset:5120
	ds_read_b64_tr_b16 v[240:241], v249 offset:7168
	ds_read_b64_tr_b16 v[242:243], v249 offset:5632
	ds_read_b64_tr_b16 v[244:245], v249 offset:7680
	s_add_i32 s30, s85, s34
	s_add_i32 m0, s30, 0x8000
	s_nop 0
	global_load_lds_dwordx4 v222, s[2:3] sc1
	s_waitcnt lgkmcnt(8)
	v_mfma_f32_32x32x16_bf16 v[112:127], v[234:237], v[128:131], v[112:127]
	v_mfma_f32_32x32x16_bf16 v[96:111], v[234:237], v[132:135], v[96:111]
	ds_read_b64_tr_b16 v[128:129], v249 offset:16384
	ds_read_b64_tr_b16 v[130:131], v249 offset:18432
	ds_read_b64_tr_b16 v[132:133], v249 offset:16896
	ds_read_b64_tr_b16 v[134:135], v249 offset:18944
	s_add_i32 s30, s85, s34
	s_add_i32 m0, s30, 0xa000
	s_nop 0
	global_load_lds_dwordx4 v221, s[2:3] sc1
	s_waitcnt lgkmcnt(8)
	v_mfma_f32_32x32x16_bf16 v[80:95], v[230:233], v[136:139], v[80:95]
	v_mfma_f32_32x32x16_bf16 v[64:79], v[230:233], v[140:143], v[64:79]
	ds_read_b64_tr_b16 v[136:137], v249 offset:20480
	ds_read_b64_tr_b16 v[138:139], v249 offset:22528
	ds_read_b64_tr_b16 v[140:141], v249 offset:20992
	ds_read_b64_tr_b16 v[142:143], v249 offset:23040
	s_add_i32 s30, s85, s34
	s_add_i32 m0, s30, 0xc000
	s_nop 0
	global_load_lds_dwordx4 v246, s[2:3] sc1
	s_waitcnt lgkmcnt(8)
	v_mfma_f32_32x32x16_bf16 v[80:95], v[234:237], v[238:241], v[80:95]
	v_mfma_f32_32x32x16_bf16 v[64:79], v[234:237], v[242:245], v[64:79]
	ds_read_b64_tr_b16 v[238:239], v249 offset:17408
	ds_read_b64_tr_b16 v[240:241], v249 offset:19456
	ds_read_b64_tr_b16 v[242:243], v249 offset:17920
	ds_read_b64_tr_b16 v[244:245], v249 offset:19968
	s_add_i32 s30, s85, s34
	s_add_i32 m0, s30, 0xe000
	s_nop 0
	global_load_lds_dwordx4 v247, s[2:3] sc1
	s_waitcnt lgkmcnt(8)
	v_mfma_f32_32x32x16_bf16 v[32:47], v[230:233], v[128:131], v[32:47]
	v_mfma_f32_32x32x16_bf16 v[16:31], v[230:233], v[132:135], v[16:31]
	ds_read_b64_tr_b16 v[128:129], v249 offset:21504
	ds_read_b64_tr_b16 v[130:131], v249 offset:23552
	ds_read_b64_tr_b16 v[132:133], v249 offset:22016
	ds_read_b64_tr_b16 v[134:135], v249 offset:24064
	s_mov_b32 m0, s34
	s_nop 0
	global_load_lds_dwordx4 v225, s[86:87] sc1
	s_waitcnt lgkmcnt(8)
	v_mfma_f32_32x32x16_bf16 v[32:47], v[234:237], v[136:139], v[32:47]
	v_mfma_f32_32x32x16_bf16 v[16:31], v[234:237], v[140:143], v[16:31]
	s_add_i32 m0, s34, 0x2000
	s_nop 0
	global_load_lds_dwordx4 v223, s[86:87] sc1
	s_waitcnt lgkmcnt(0)
	v_mfma_f32_32x32x16_bf16 v[48:63], v[230:233], v[238:241], v[48:63]
	v_mfma_f32_32x32x16_bf16 v[0:15], v[230:233], v[242:245], v[0:15]
	v_mfma_f32_32x32x16_bf16 v[48:63], v[234:237], v[128:131], v[48:63]
	v_mfma_f32_32x32x16_bf16 v[0:15], v[234:237], v[132:135], v[0:15]
	s_add_i32 s84, s84, 0x8000
	s_cmp_eq_u32 s84, 0x18000
	s_cselect_b32 s84, 0, s84
	s_add_i32 s40, s40, 1
	s_cmpk_eq_i32 s40, 0x82
	s_cbranch_scc0 .LattnB_m1
	s_waitcnt vmcnt(0)
	s_barrier
